# phase 9: stage-2 weight tile loads (wconv super-tile, 8 x 16B per lane, nontemporal) issued during the GLA pre-pass item and consumed after it with a counted wait
# speedup vs baseline: 1.0132x; 1.0004x over previous
.LBB0_286:
	s_and_b32 s13, s53, 1
	s_xor_b32 s11, s0, 31
	s_cmp_eq_u32 s13, 0
	s_cselect_b64 s[14:15], -1, 0
	s_and_b64 s[14:15], s[14:15], exec
	s_cselect_b32 s0, s0, s11
	s_lshl_b32 s11, s0, 6
	s_xor_b32 s12, s11, 0x7ff
	s_cmp_eq_u32 s13, 0
	s_cselect_b64 vcc, -1, 0
	s_and_b64 s[14:15], vcc, exec
	s_movk_i32 s14, 0x5040
	s_cselect_b32 s14, s14, 0xffffafc0
	s_cselect_b32 s11, s11, s12
	s_lshl_b32 s10, s10, 3
	s_and_b32 s12, s53, 6
	s_or_b32 s10, s10, s12
	s_waitcnt vmcnt(4)
	v_mov_b32_e32 v0, v65
	s_or_b32 s10, s10, s13
	s_or_b32 s3, s11, s3
	s_lshl_b32 s12, s10, 5
	v_add_u32_e32 v82, v0, v190
	s_mul_hi_i32 s11, s3, 0xa080
	s_mul_i32 s3, s3, 0xa080
	v_ashrrev_i32_e32 v123, 7, v82
	s_add_u32 s10, s24, s3
	v_and_b32_e32 v127, 0x7f, v82
	s_addc_u32 s11, s25, s11
	s_lshl_b32 s2, s2, 7
	v_lshlrev_b32_e32 v104, 4, v123
	s_and_b32 s15, s2, 0x300
	v_lshlrev_b32_e32 v0, 1, v127
	v_mul_lo_u32 v1, v104, s14
	v_or3_b32 v0, s15, v0, v1
	v_add_u32_e32 v0, 0x1800, v0
	v_ashrrev_i32_e32 v1, 31, v0
	v_lshl_add_u64 v[2:3], v[0:1], 1, s[10:11]
	v_add_u32_e32 v0, s14, v0
	v_ashrrev_i32_e32 v1, 31, v0
	global_load_dword v132, v[2:3], off
	global_load_dword v131, v[2:3], off offset:2048
	v_lshl_add_u64 v[2:3], v[0:1], 1, s[10:11]
	v_add_u32_e32 v0, s14, v0
	v_ashrrev_i32_e32 v1, 31, v0
	global_load_dword v130, v[2:3], off
	global_load_dword v129, v[2:3], off offset:2048
	v_lshl_add_u64 v[2:3], v[0:1], 1, s[10:11]
	v_add_u32_e32 v0, s14, v0
	v_ashrrev_i32_e32 v1, 31, v0
	global_load_dword v126, v[2:3], off
	global_load_dword v125, v[2:3], off offset:2048
	v_lshl_add_u64 v[2:3], v[0:1], 1, s[10:11]
	v_add_u32_e32 v0, s14, v0
	v_ashrrev_i32_e32 v1, 31, v0
	global_load_dword v122, v[2:3], off
	global_load_dword v121, v[2:3], off offset:2048
	v_lshl_add_u64 v[2:3], v[0:1], 1, s[10:11]
	v_add_u32_e32 v0, s14, v0
	v_ashrrev_i32_e32 v1, 31, v0
	global_load_dword v119, v[2:3], off
	global_load_dword v118, v[2:3], off offset:2048
	v_lshl_add_u64 v[2:3], v[0:1], 1, s[10:11]
	v_add_u32_e32 v0, s14, v0
	v_ashrrev_i32_e32 v1, 31, v0
	global_load_dword v116, v[2:3], off
	global_load_dword v115, v[2:3], off offset:2048
	v_lshl_add_u64 v[2:3], v[0:1], 1, s[10:11]
	v_add_u32_e32 v0, s14, v0
	v_ashrrev_i32_e32 v1, 31, v0
	global_load_dword v113, v[2:3], off
	global_load_dword v112, v[2:3], off offset:2048
	v_lshl_add_u64 v[2:3], v[0:1], 1, s[10:11]
	v_add_u32_e32 v0, s14, v0
	v_ashrrev_i32_e32 v1, 31, v0
	global_load_dword v110, v[2:3], off
	global_load_dword v109, v[2:3], off offset:2048
	v_lshl_add_u64 v[2:3], v[0:1], 1, s[10:11]
	v_add_u32_e32 v0, s14, v0
	v_ashrrev_i32_e32 v1, 31, v0
	global_load_dword v107, v[2:3], off
	global_load_dword v106, v[2:3], off offset:2048
	v_lshl_add_u64 v[2:3], v[0:1], 1, s[10:11]
	v_add_u32_e32 v0, s14, v0
	v_ashrrev_i32_e32 v1, 31, v0
	global_load_dword v103, v[2:3], off
	global_load_dword v102, v[2:3], off offset:2048
	v_lshl_add_u64 v[2:3], v[0:1], 1, s[10:11]
	v_add_u32_e32 v0, s14, v0
	v_ashrrev_i32_e32 v1, 31, v0
	global_load_dword v100, v[2:3], off
	global_load_dword v99, v[2:3], off offset:2048
	v_lshl_add_u64 v[2:3], v[0:1], 1, s[10:11]
	v_add_u32_e32 v0, s14, v0
	v_ashrrev_i32_e32 v1, 31, v0
	global_load_dword v97, v[2:3], off
	global_load_dword v96, v[2:3], off offset:2048
	v_lshl_add_u64 v[2:3], v[0:1], 1, s[10:11]
	v_add_u32_e32 v0, s14, v0
	v_ashrrev_i32_e32 v1, 31, v0
	global_load_dword v94, v[2:3], off
	global_load_dword v93, v[2:3], off offset:2048
	v_lshl_add_u64 v[2:3], v[0:1], 1, s[10:11]
	v_add_u32_e32 v0, s14, v0
	v_ashrrev_i32_e32 v1, 31, v0
	global_load_dword v91, v[2:3], off
	global_load_dword v90, v[2:3], off offset:2048
	v_lshl_add_u64 v[2:3], v[0:1], 1, s[10:11]
	v_add_u32_e32 v0, s14, v0
	s_or_b32 s2, s13, s22
	v_ashrrev_i32_e32 v1, 31, v0
	s_ashr_i32 s3, s2, 31
	v_readlane_b32 s72, v252, 9
	v_lshl_add_u64 v[0:1], v[0:1], 1, s[10:11]
	s_lshl_b64 s[10:11], s[2:3], 16
	v_readlane_b32 s86, v252, 23
	v_readlane_b32 s87, v252, 24
	s_add_u32 s10, s86, s10
	s_addc_u32 s11, s87, s11
	s_lshl_b32 s14, s15, 2
	s_add_u32 s10, s10, s14
	s_addc_u32 s11, s11, 0
	v_lshlrev_b32_e32 v64, 3, v127
	global_load_dword v88, v[2:3], off
	global_load_dword v87, v[2:3], off offset:2048
	global_load_dword v85, v[0:1], off
	global_load_dword v84, v[0:1], off offset:2048
	v_lshl_add_u64 v[0:1], s[10:11], 0, v[64:65]
	global_load_dwordx2 v[30:31], v64, s[10:11]
	s_movk_i32 s10, 0x2000
	v_add_co_u32_e64 v2, s[62:63], s10, v0
	s_movk_i32 s10, 0x4000
	s_nop 0
	v_addc_co_u32_e64 v3, s[62:63], 0, v1, s[62:63]
	global_load_dwordx2 v[32:33], v[2:3], off offset:-4096
	global_load_dwordx2 v[26:27], v[2:3], off
	v_add_co_u32_e64 v2, s[62:63], s10, v0
	s_movk_i32 s10, 0x6000
	s_nop 0
	v_addc_co_u32_e64 v3, s[62:63], 0, v1, s[62:63]
	global_load_dwordx2 v[28:29], v[2:3], off offset:-4096
	global_load_dwordx2 v[22:23], v[2:3], off
	v_add_co_u32_e64 v2, s[62:63], s10, v0
	s_mov_b32 s10, 0x8000
	s_nop 0
	v_addc_co_u32_e64 v3, s[62:63], 0, v1, s[62:63]
	global_load_dwordx2 v[24:25], v[2:3], off offset:-4096
	global_load_dwordx2 v[18:19], v[2:3], off
	v_add_co_u32_e64 v2, s[62:63], s10, v0
	s_mov_b32 s10, 0xc000
	s_nop 0
	v_addc_co_u32_e64 v3, s[62:63], 0, v1, s[62:63]
	global_load_dwordx2 v[20:21], v[2:3], off offset:-4096
	global_load_dwordx2 v[16:17], v[2:3], off
	v_add_co_u32_e64 v2, s[62:63], s89, v0
	v_readlane_b32 s73, v252, 10
	s_nop 0
	v_addc_co_u32_e64 v3, s[62:63], 0, v1, s[62:63]
	v_readlane_b32 s74, v252, 11
	v_readlane_b32 s75, v252, 12
	v_readlane_b32 s76, v252, 13
	v_readlane_b32 s77, v252, 14
	v_readlane_b32 s78, v252, 15
	v_readlane_b32 s79, v252, 16
	v_readlane_b32 s80, v252, 17
	v_readlane_b32 s81, v252, 18
	v_readlane_b32 s82, v252, 19
	v_readlane_b32 s83, v252, 20
	v_readlane_b32 s84, v252, 21
	v_readlane_b32 s85, v252, 22
	global_load_dwordx2 v[14:15], v[2:3], off offset:-4096
	global_load_dwordx2 v[10:11], v[2:3], off
	v_add_co_u32_e64 v2, s[62:63], s10, v0
	s_mov_b32 s10, 0xe000
	s_nop 0
	v_addc_co_u32_e64 v3, s[62:63], 0, v1, s[62:63]
	s_lshl_b64 s[2:3], s[2:3], 12
	v_readlane_b32 s72, v252, 25
	global_load_dwordx2 v[12:13], v[2:3], off offset:-4096
	global_load_dwordx2 v[8:9], v[2:3], off
	v_add_co_u32_e64 v2, s[62:63], s10, v0
	v_readlane_b32 s73, v252, 26
	s_add_u32 s2, s72, s2
	v_addc_co_u32_e64 v3, s[62:63], 0, v1, s[62:63]
	s_mov_b32 s10, 0xf000
	s_addc_u32 s3, s73, s3
	v_add_co_u32_e64 v0, s[62:63], s10, v0
	s_add_u32 s2, s2, s14
	s_nop 0
	v_addc_co_u32_e64 v1, s[62:63], 0, v1, s[62:63]
	s_addc_u32 s3, s3, 0
	global_load_dwordx2 v[6:7], v[2:3], off offset:-4096
	global_load_dwordx2 v[4:5], v[2:3], off
	v_sub_u32_e32 v34, 63, v104
	global_load_dwordx2 v[2:3], v[0:1], off
	v_cndmask_b32_e32 v34, v34, v104, vcc
	global_load_dwordx2 v[0:1], v64, s[2:3]
	s_lshl_b32 s2, s13, 6
	s_add_i32 s10, s2, 0
	s_add_i32 s10, s10, 0x19800
	v_writelane_b32 v255, s34, 59
	v_writelane_b32 v255, s28, 58
	s_mul_i32 s32, s53, s42
	v_readlane_b32 s34, v255, 17
	s_nop 1
	s_add_i32 s32, s32, s34
	s_min_u32 s32, s32, 0x6ff
	s_mov_b64 s[98:99], s[54:55]
	s_movk_i32 s28, 0x1800
	s_mul_i32 s100, s32, 0xaab
	s_lshr_b32 s100, s100, 16
	s_mul_i32 s101, s100, 24
	s_sub_u32 s101, s32, s101
	s_cmp_lt_u32 s32, 0x300
	s_cbranch_scc1 .Lwp_go
	s_movk_i32 s28, 0x800
	s_sub_u32 s34, s32, 0x300
	s_cmp_lt_u32 s32, 0x600
	s_cbranch_scc0 .Lwp_out
	s_lshr_b32 s100, s34, 8
	v_readlane_b32 s101, v255, 35
	s_nop 1
	s_add_u32 s100, s100, s101
	s_lshl_b32 s100, s100, 24
	v_readlane_b32 s98, v252, 35
	v_readlane_b32 s99, v252, 36
	s_nop 1
	s_add_u32 s98, s98, s100
	s_addc_u32 s99, s99, 0
	s_and_b32 s34, s34, 0xff
	s_branch .Lwp_t8
.Lwp_out:
	s_mov_b64 s[98:99], s[26:27]
	s_sub_u32 s34, s32, 0x600
.Lwp_t8:
	s_lshr_b32 s100, s34, 3
	s_and_b32 s101, s34, 7
.Lwp_go:
	s_mul_i32 s100, s100, s28
	s_lshl_b32 s100, s100, 8
	s_lshl_b32 s101, s101, 10
	s_add_u32 s100, s100, s101
	s_add_u32 s98, s98, s100
	s_addc_u32 s99, s99, 0
	v_lshrrev_b32_e32 v224, 6, v190
	v_mul_lo_u32 v224, v224, s28
	v_and_b32_e32 v225, 63, v190
	v_lshl_add_u32 v224, v225, 2, v224
	v_lshlrev_b32_e32 v224, 2, v224
	s_lshl_b32 s100, s28, 5
	s_nop 1
	global_load_dwordx4 v[192:195], v224, s[98:99] nt
	v_add_u32_e32 v224, s100, v224
	global_load_dwordx4 v[196:199], v224, s[98:99] nt
	v_add_u32_e32 v224, s100, v224
	global_load_dwordx4 v[200:203], v224, s[98:99] nt
	v_add_u32_e32 v224, s100, v224
	global_load_dwordx4 v[204:207], v224, s[98:99] nt
	v_add_u32_e32 v224, s100, v224
	global_load_dwordx4 v[208:211], v224, s[98:99] nt
	v_add_u32_e32 v224, s100, v224
	global_load_dwordx4 v[212:215], v224, s[98:99] nt
	v_add_u32_e32 v224, s100, v224
	global_load_dwordx4 v[216:219], v224, s[98:99] nt
	v_add_u32_e32 v224, s100, v224
	global_load_dwordx4 v[220:223], v224, s[98:99] nt
	v_readlane_b32 s34, v255, 59
	v_readlane_b32 s28, v255, 58
	s_waitcnt lgkmcnt(0)
	s_barrier
	v_lshl_add_u32 v46, v34, 7, s10
	ds_read_b128 v[34:37], v46
	ds_read_b128 v[38:41], v46 offset:16
	ds_read_b128 v[42:45], v46 offset:32
	ds_read_b128 v[46:49], v46 offset:48
	v_or_b32_e32 v128, 1, v104
	v_or_b32_e32 v124, 2, v104
	v_or_b32_e32 v120, 3, v104
	v_or_b32_e32 v117, 4, v104
	s_mov_b32 s2, 0x3d800000
	v_or_b32_e32 v114, 5, v104
	v_or_b32_e32 v111, 6, v104
	v_or_b32_e32 v108, 7, v104
	v_or_b32_e32 v105, 8, v104
	v_or_b32_e32 v101, 9, v104
	v_or_b32_e32 v98, 10, v104
	v_or_b32_e32 v95, 11, v104
	v_or_b32_e32 v92, 12, v104
	v_or_b32_e32 v89, 13, v104
	v_or_b32_e32 v86, 14, v104
	v_or_b32_e32 v83, 15, v104
	v_readlane_b32 s74, v252, 27
	v_readlane_b32 s75, v252, 28
	v_readlane_b32 s76, v252, 29
	v_readlane_b32 s77, v252, 30
	v_readlane_b32 s78, v252, 31
	v_readlane_b32 s79, v252, 32
	v_readlane_b32 s80, v252, 33
	v_readlane_b32 s81, v252, 34
	v_readlane_b32 s82, v252, 35
	v_readlane_b32 s83, v252, 36
	v_readlane_b32 s84, v252, 37
	v_readlane_b32 s85, v252, 38
	v_readlane_b32 s86, v252, 39
	v_readlane_b32 s87, v252, 40
	s_waitcnt vmcnt(8) lgkmcnt(3)
	v_fma_f32 v50, v34, v30, v0
	v_fmac_f32_e32 v50, v35, v32
	v_fmac_f32_e32 v50, v36, v26
	v_fmac_f32_e32 v50, v37, v28
	s_waitcnt lgkmcnt(2)
	v_fmac_f32_e32 v50, v38, v22
	v_fmac_f32_e32 v50, v39, v24
	v_fmac_f32_e32 v50, v40, v18
	v_fmac_f32_e32 v50, v41, v20
	s_waitcnt lgkmcnt(1)
	v_fmac_f32_e32 v50, v42, v16
	v_fmac_f32_e32 v50, v43, v14
	v_fmac_f32_e32 v50, v44, v10
	v_fma_f32 v51, v34, v31, v1
	v_fmac_f32_e32 v50, v45, v12
	v_fmac_f32_e32 v51, v35, v33
	s_waitcnt lgkmcnt(0)
	v_fmac_f32_e32 v50, v46, v8
	v_fmac_f32_e32 v51, v36, v27
	v_fmac_f32_e32 v50, v47, v6
	v_fmac_f32_e32 v51, v37, v29
	v_fmac_f32_e32 v50, v48, v4
	v_fmac_f32_e32 v51, v38, v23
	v_fmac_f32_e32 v50, v49, v2
	v_fmac_f32_e32 v51, v39, v25
	v_mul_f32_e64 v35, |v50|, s90
	v_fmac_f32_e32 v51, v40, v19
	v_exp_f32_e32 v35, v35
	v_fmac_f32_e32 v51, v41, v21
	v_fmac_f32_e32 v51, v42, v17
	v_fmac_f32_e32 v51, v43, v15
	v_fmac_f32_e32 v51, v44, v11
	v_add_f32_e32 v35, 1.0, v35
	v_fmac_f32_e32 v51, v45, v13
	v_cmp_gt_f32_e64 s[62:63], s92, v35
	v_fmac_f32_e32 v51, v46, v9
	v_fmac_f32_e32 v51, v47, v7
	v_cndmask_b32_e64 v36, 0, 32, s[62:63]
	v_ldexp_f32 v35, v35, v36
	v_fmac_f32_e32 v51, v48, v5
	v_log_f32_e32 v35, v35
	v_fmac_f32_e32 v51, v49, v3
	v_mul_f32_e64 v37, |v51|, s90
	v_exp_f32_e32 v37, v37
	v_mul_f32_e32 v36, 0x3f317217, v35
	v_fma_f32 v36, v35, s41, -v36
	v_fmac_f32_e32 v36, 0x3377d1cf, v35
	v_fmac_f32_e32 v36, 0x3f317217, v35
	v_cmp_lt_f32_e64 s[64:65], |v35|, s68
	v_add_f32_e32 v37, 1.0, v37
	v_min_f32_e32 v34, 0, v50
	v_cndmask_b32_e64 v35, v35, v36, s[64:65]
	v_cndmask_b32_e64 v36, 0, v187, s[62:63]
	v_cmp_gt_f32_e64 s[62:63], s92, v37
	v_sub_f32_e32 v36, v35, v36
	v_min_f32_e32 v35, 0, v51
	v_cndmask_b32_e64 v38, 0, 32, s[62:63]
	v_ldexp_f32 v37, v37, v38
	v_log_f32_e32 v37, v37
	s_nop 0
	v_mul_f32_e32 v38, 0x3f317217, v37
	v_fma_f32 v38, v37, s41, -v38
	v_fmac_f32_e32 v38, 0x3377d1cf, v37
	v_fmac_f32_e32 v38, 0x3f317217, v37
	v_cmp_lt_f32_e64 s[64:65], |v37|, s68
	s_nop 1
	v_cndmask_b32_e64 v37, v37, v38, s[64:65]
	v_cndmask_b32_e64 v38, 0, v187, s[62:63]
	v_sub_f32_e32 v37, v37, v38
	v_sub_u32_e32 v38, 63, v128
	v_cndmask_b32_e32 v38, v38, v128, vcc
	v_lshl_add_u32 v50, v38, 7, s10
	ds_read_b128 v[38:41], v50
	ds_read_b128 v[42:45], v50 offset:16
	ds_read_b128 v[46:49], v50 offset:32
	ds_read_b128 v[50:53], v50 offset:48
	v_pk_add_f32 v[34:35], v[34:35], v[36:37] neg_lo:[0,1] neg_hi:[0,1]
	s_waitcnt lgkmcnt(3)
	v_fma_f32 v54, v38, v30, v0
	v_fmac_f32_e32 v54, v39, v32
	v_fmac_f32_e32 v54, v40, v26
	v_fmac_f32_e32 v54, v41, v28
	s_waitcnt lgkmcnt(2)
	v_fmac_f32_e32 v54, v42, v22
	v_fmac_f32_e32 v54, v43, v24
	v_fmac_f32_e32 v54, v44, v18
	v_fmac_f32_e32 v54, v45, v20
	s_waitcnt lgkmcnt(1)
	v_fmac_f32_e32 v54, v46, v16
	v_fmac_f32_e32 v54, v47, v14
	v_fmac_f32_e32 v54, v48, v10
	v_fma_f32 v55, v38, v31, v1
	v_fmac_f32_e32 v54, v49, v12
	v_fmac_f32_e32 v55, v39, v33
	s_waitcnt lgkmcnt(0)
	v_fmac_f32_e32 v54, v50, v8
	v_fmac_f32_e32 v55, v40, v27
	v_fmac_f32_e32 v54, v51, v6
	v_fmac_f32_e32 v55, v41, v29
	v_fmac_f32_e32 v54, v52, v4
	v_fmac_f32_e32 v55, v42, v23
	v_fmac_f32_e32 v54, v53, v2
	v_fmac_f32_e32 v55, v43, v25
	v_mul_f32_e64 v39, |v54|, s90
	v_fmac_f32_e32 v55, v44, v19
	v_exp_f32_e32 v39, v39
	v_fmac_f32_e32 v55, v45, v21
	v_fmac_f32_e32 v55, v46, v17
	v_fmac_f32_e32 v55, v47, v15
	v_fmac_f32_e32 v55, v48, v11
	v_add_f32_e32 v39, 1.0, v39
	v_fmac_f32_e32 v55, v49, v13
	v_cmp_gt_f32_e64 s[62:63], s92, v39
	v_fmac_f32_e32 v55, v50, v9
	v_fmac_f32_e32 v55, v51, v7
	v_cndmask_b32_e64 v40, 0, 32, s[62:63]
	v_ldexp_f32 v39, v39, v40
	v_fmac_f32_e32 v55, v52, v5
	v_log_f32_e32 v39, v39
	v_fmac_f32_e32 v55, v53, v3
	v_mul_f32_e64 v41, |v55|, s90
	v_exp_f32_e32 v41, v41
	v_mul_f32_e32 v40, 0x3f317217, v39
	v_fma_f32 v40, v39, s41, -v40
	v_fmac_f32_e32 v40, 0x3377d1cf, v39
	v_fmac_f32_e32 v40, 0x3f317217, v39
	v_cmp_lt_f32_e64 s[64:65], |v39|, s68
	v_add_f32_e32 v41, 1.0, v41
	v_min_f32_e32 v38, 0, v54
	v_cndmask_b32_e64 v39, v39, v40, s[64:65]
	v_cndmask_b32_e64 v40, 0, v187, s[62:63]
	v_cmp_gt_f32_e64 s[62:63], s92, v41
	v_sub_f32_e32 v40, v39, v40
	v_min_f32_e32 v39, 0, v55
	v_cndmask_b32_e64 v42, 0, 32, s[62:63]
	v_ldexp_f32 v41, v41, v42
	v_log_f32_e32 v41, v41
	s_nop 0
	v_mul_f32_e32 v42, 0x3f317217, v41
	v_fma_f32 v42, v41, s41, -v42
	v_fmac_f32_e32 v42, 0x3377d1cf, v41
	v_fmac_f32_e32 v42, 0x3f317217, v41
	v_cmp_lt_f32_e64 s[64:65], |v41|, s68
	s_nop 1
	v_cndmask_b32_e64 v41, v41, v42, s[64:65]
	v_cndmask_b32_e64 v42, 0, v187, s[62:63]
	v_sub_f32_e32 v41, v41, v42
	v_sub_u32_e32 v42, 63, v124
	v_cndmask_b32_e32 v42, v42, v124, vcc
	v_lshl_add_u32 v54, v42, 7, s10
	ds_read_b128 v[42:45], v54
	ds_read_b128 v[46:49], v54 offset:16
	ds_read_b128 v[50:53], v54 offset:32
	ds_read_b128 v[54:57], v54 offset:48
	s_waitcnt lgkmcnt(3)
	v_fma_f32 v58, v42, v30, v0
	v_fmac_f32_e32 v58, v43, v32
	v_fmac_f32_e32 v58, v44, v26
	v_fmac_f32_e32 v58, v45, v28
	s_waitcnt lgkmcnt(2)
	v_fmac_f32_e32 v58, v46, v22
	v_fmac_f32_e32 v58, v47, v24
	v_fmac_f32_e32 v58, v48, v18
	v_fmac_f32_e32 v58, v49, v20
	s_waitcnt lgkmcnt(1)
	v_fmac_f32_e32 v58, v50, v16
	v_fmac_f32_e32 v58, v51, v14
	v_fmac_f32_e32 v58, v52, v10
	v_fmac_f32_e32 v58, v53, v12
	s_waitcnt lgkmcnt(0)
	v_fmac_f32_e32 v58, v54, v8
	v_fmac_f32_e32 v58, v55, v6
	v_fmac_f32_e32 v58, v56, v4
	v_fma_f32 v42, v42, v31, v1
	v_fmac_f32_e32 v58, v57, v2
	v_fmac_f32_e32 v42, v43, v33
	v_mul_f32_e64 v43, |v58|, s90
	v_exp_f32_e32 v43, v43
	v_fmac_f32_e32 v42, v44, v27
	v_fmac_f32_e32 v42, v45, v29
	v_fmac_f32_e32 v42, v46, v23
	v_add_f32_e32 v43, 1.0, v43
	v_cmp_gt_f32_e64 s[62:63], s92, v43
	v_fmac_f32_e32 v42, v47, v25
	v_fmac_f32_e32 v42, v48, v19
	v_cndmask_b32_e64 v45, 0, 32, s[62:63]
	v_ldexp_f32 v43, v43, v45
	v_fmac_f32_e32 v42, v49, v21
	v_log_f32_e32 v43, v43
	v_fmac_f32_e32 v42, v50, v17
	v_fmac_f32_e32 v42, v51, v15
	v_fmac_f32_e32 v42, v52, v11
	v_fmac_f32_e32 v42, v53, v13
	v_mul_f32_e32 v45, 0x3f317217, v43
	v_fmac_f32_e32 v42, v54, v9
	v_fma_f32 v45, v43, s41, -v45
	v_fmac_f32_e32 v42, v55, v7
	v_fmac_f32_e32 v45, 0x3377d1cf, v43
	v_fmac_f32_e32 v42, v56, v5
	v_fmac_f32_e32 v45, 0x3f317217, v43
	v_cmp_lt_f32_e64 s[64:65], |v43|, s68
	v_fmac_f32_e32 v42, v57, v3
	v_min_f32_e32 v44, 0, v58
	v_cndmask_b32_e64 v43, v43, v45, s[64:65]
	v_cndmask_b32_e64 v45, 0, v187, s[62:63]
	v_sub_f32_e32 v46, v43, v45
	v_min_f32_e32 v45, 0, v42
	v_mul_f32_e64 v42, |v42|, s90
	v_exp_f32_e32 v42, v42
	s_nop 0
	v_add_f32_e32 v42, 1.0, v42
	v_cmp_gt_f32_e64 s[62:63], s92, v42
	s_nop 1
	v_cndmask_b32_e64 v43, 0, 32, s[62:63]
	v_ldexp_f32 v42, v42, v43
	v_log_f32_e32 v42, v42
	s_nop 0
	v_mul_f32_e32 v43, 0x3f317217, v42
	v_fma_f32 v43, v42, s41, -v43
	v_fmac_f32_e32 v43, 0x3377d1cf, v42
	v_fmac_f32_e32 v43, 0x3f317217, v42
	v_cmp_lt_f32_e64 s[64:65], |v42|, s68
	s_nop 1
	v_cndmask_b32_e64 v42, v42, v43, s[64:65]
	v_cndmask_b32_e64 v43, 0, v187, s[62:63]
	v_sub_f32_e32 v47, v42, v43
	v_sub_u32_e32 v42, 63, v120
	v_cndmask_b32_e32 v42, v42, v120, vcc
	v_lshl_add_u32 v42, v42, 7, s10
	ds_read_b128 v[48:51], v42
	ds_read_b128 v[52:55], v42 offset:16
	ds_read_b128 v[56:59], v42 offset:32
	ds_read_b128 v[60:63], v42 offset:48
	s_waitcnt lgkmcnt(3)
	v_fma_f32 v42, v48, v30, v0
	v_fmac_f32_e32 v42, v49, v32
	v_fmac_f32_e32 v42, v50, v26
	v_fmac_f32_e32 v42, v51, v28
	s_waitcnt lgkmcnt(2)
	v_fmac_f32_e32 v42, v52, v22
	v_fmac_f32_e32 v42, v53, v24
	v_fmac_f32_e32 v42, v54, v18
	v_fmac_f32_e32 v42, v55, v20
	s_waitcnt lgkmcnt(1)
	v_fmac_f32_e32 v42, v56, v16
	v_fmac_f32_e32 v42, v57, v14
	v_fmac_f32_e32 v42, v58, v10
	v_fmac_f32_e32 v42, v59, v12
	s_waitcnt lgkmcnt(0)
	v_fmac_f32_e32 v42, v60, v8
	v_fmac_f32_e32 v42, v61, v6
	v_fmac_f32_e32 v42, v62, v4
	v_fmac_f32_e32 v42, v63, v2
	v_fma_f32 v43, v48, v31, v1
	v_min_f32_e32 v48, 0, v42
	v_mul_f32_e64 v42, |v42|, s90
	v_exp_f32_e32 v42, v42
	v_fmac_f32_e32 v43, v49, v33
	v_fmac_f32_e32 v43, v50, v27
	v_fmac_f32_e32 v43, v51, v29
	v_add_f32_e32 v42, 1.0, v42
	v_fmac_f32_e32 v43, v52, v23
	v_cmp_gt_f32_e64 s[62:63], s92, v42
	v_fmac_f32_e32 v43, v53, v25
	v_fmac_f32_e32 v43, v54, v19
	v_cndmask_b32_e64 v49, 0, 32, s[62:63]
	v_ldexp_f32 v42, v42, v49
	v_fmac_f32_e32 v43, v55, v21
	v_log_f32_e32 v42, v42
	v_fmac_f32_e32 v43, v56, v17
	v_fmac_f32_e32 v43, v57, v15
	v_fmac_f32_e32 v43, v58, v11
	v_fmac_f32_e32 v43, v59, v13
	v_mul_f32_e32 v49, 0x3f317217, v42
	v_fmac_f32_e32 v43, v60, v9
	v_fma_f32 v49, v42, s41, -v49
	v_fmac_f32_e32 v43, v61, v7
	v_fmac_f32_e32 v49, 0x3377d1cf, v42
	v_fmac_f32_e32 v43, v62, v5
	v_fmac_f32_e32 v49, 0x3f317217, v42
	v_cmp_lt_f32_e64 s[64:65], |v42|, s68
	v_fmac_f32_e32 v43, v63, v3
	s_nop 0
	v_cndmask_b32_e64 v42, v42, v49, s[64:65]
	v_cndmask_b32_e64 v49, 0, v187, s[62:63]
	v_sub_f32_e32 v50, v42, v49
	v_mul_f32_e64 v42, |v43|, s90
	v_exp_f32_e32 v42, v42
	v_min_f32_e32 v49, 0, v43
	v_add_f32_e32 v42, 1.0, v42
	v_cmp_gt_f32_e64 s[62:63], s92, v42
	s_nop 1
	v_cndmask_b32_e64 v43, 0, 32, s[62:63]
	v_ldexp_f32 v42, v42, v43
	v_log_f32_e32 v42, v42
	s_nop 0
	v_mul_f32_e32 v43, 0x3f317217, v42
	v_fma_f32 v43, v42, s41, -v43
	v_fmac_f32_e32 v43, 0x3377d1cf, v42
	v_fmac_f32_e32 v43, 0x3f317217, v42
	v_cmp_lt_f32_e64 s[64:65], |v42|, s68
	s_nop 1
	v_cndmask_b32_e64 v42, v42, v43, s[64:65]
	v_cndmask_b32_e64 v43, 0, v187, s[62:63]
	v_sub_f32_e32 v51, v42, v43
	v_sub_u32_e32 v42, 63, v117
	v_cndmask_b32_e32 v42, v42, v117, vcc
	v_lshl_add_u32 v42, v42, 7, s10
	ds_read_b128 v[52:55], v42
	ds_read_b128 v[56:59], v42 offset:16
	ds_read_b128 v[60:63], v42 offset:32
	ds_read_b128 v[66:69], v42 offset:48
	s_waitcnt lgkmcnt(3)
	v_fma_f32 v42, v52, v30, v0
	v_fmac_f32_e32 v42, v53, v32
	v_fmac_f32_e32 v42, v54, v26
	v_fmac_f32_e32 v42, v55, v28
	s_waitcnt lgkmcnt(2)
	v_fmac_f32_e32 v42, v56, v22
	v_fmac_f32_e32 v42, v57, v24
	v_fmac_f32_e32 v42, v58, v18
	v_fmac_f32_e32 v42, v59, v20
	s_waitcnt lgkmcnt(1)
	v_fmac_f32_e32 v42, v60, v16
	v_fmac_f32_e32 v42, v61, v14
	v_fmac_f32_e32 v42, v62, v10
	v_fmac_f32_e32 v42, v63, v12
	s_waitcnt lgkmcnt(0)
	v_fmac_f32_e32 v42, v66, v8
	v_fmac_f32_e32 v42, v67, v6
	v_fmac_f32_e32 v42, v68, v4
	v_fmac_f32_e32 v42, v69, v2
	v_fma_f32 v43, v52, v31, v1
	v_min_f32_e32 v52, 0, v42
	v_mul_f32_e64 v42, |v42|, s90
	v_exp_f32_e32 v42, v42
	v_fmac_f32_e32 v43, v53, v33
	v_fmac_f32_e32 v43, v54, v27
	v_fmac_f32_e32 v43, v55, v29
	v_add_f32_e32 v42, 1.0, v42
	v_fmac_f32_e32 v43, v56, v23
	v_cmp_gt_f32_e64 s[62:63], s92, v42
	v_fmac_f32_e32 v43, v57, v25
	v_fmac_f32_e32 v43, v58, v19
	v_cndmask_b32_e64 v53, 0, 32, s[62:63]
	v_ldexp_f32 v42, v42, v53
	v_fmac_f32_e32 v43, v59, v21
	v_log_f32_e32 v42, v42
	v_fmac_f32_e32 v43, v60, v17
	v_fmac_f32_e32 v43, v61, v15
	v_fmac_f32_e32 v43, v62, v11
	v_fmac_f32_e32 v43, v63, v13
	v_mul_f32_e32 v53, 0x3f317217, v42
	v_fmac_f32_e32 v43, v66, v9
	v_fma_f32 v53, v42, s41, -v53
	v_fmac_f32_e32 v43, v67, v7
	v_fmac_f32_e32 v53, 0x3377d1cf, v42
	v_fmac_f32_e32 v43, v68, v5
	v_fmac_f32_e32 v53, 0x3f317217, v42
	v_cmp_lt_f32_e64 s[64:65], |v42|, s68
	v_fmac_f32_e32 v43, v69, v3
	s_nop 0
	v_cndmask_b32_e64 v42, v42, v53, s[64:65]
	v_cndmask_b32_e64 v53, 0, v187, s[62:63]
	v_sub_f32_e32 v54, v42, v53
	v_mul_f32_e64 v42, |v43|, s90
	v_exp_f32_e32 v42, v42
	v_min_f32_e32 v53, 0, v43
	v_add_f32_e32 v42, 1.0, v42
	v_cmp_gt_f32_e64 s[62:63], s92, v42
	s_nop 1
	v_cndmask_b32_e64 v43, 0, 32, s[62:63]
	v_ldexp_f32 v42, v42, v43
	v_log_f32_e32 v42, v42
	s_nop 0
	v_mul_f32_e32 v43, 0x3f317217, v42
	v_fma_f32 v43, v42, s41, -v43
	v_fmac_f32_e32 v43, 0x3377d1cf, v42
	v_fmac_f32_e32 v43, 0x3f317217, v42
	v_cmp_lt_f32_e64 s[64:65], |v42|, s68
	s_nop 1
	v_cndmask_b32_e64 v42, v42, v43, s[64:65]
	v_cndmask_b32_e64 v43, 0, v187, s[62:63]
	v_sub_f32_e32 v55, v42, v43
	v_pk_fma_f32 v[42:43], v[34:35], s[2:3], 0 op_sel_hi:[1,0,0]
	v_pk_add_f32 v[34:35], v[38:39], v[40:41] neg_lo:[0,1] neg_hi:[0,1]
	s_nop 0
	v_pk_fma_f32 v[40:41], v[34:35], s[2:3], v[42:43] op_sel_hi:[1,0,1]
	v_pk_add_f32 v[34:35], v[44:45], v[46:47] neg_lo:[0,1] neg_hi:[0,1]
	v_sub_u32_e32 v44, 63, v114
	v_cndmask_b32_e32 v44, v44, v114, vcc
	v_pk_fma_f32 v[38:39], v[34:35], s[2:3], v[40:41] op_sel_hi:[1,0,1]
	v_pk_add_f32 v[34:35], v[48:49], v[50:51] neg_lo:[0,1] neg_hi:[0,1]
	v_lshl_add_u32 v56, v44, 7, s10
	v_pk_fma_f32 v[36:37], v[34:35], s[2:3], v[38:39] op_sel_hi:[1,0,1]
	v_pk_add_f32 v[34:35], v[52:53], v[54:55] neg_lo:[0,1] neg_hi:[0,1]
	ds_read_b128 v[44:47], v56
	ds_read_b128 v[48:51], v56 offset:16
	ds_read_b128 v[52:55], v56 offset:32
	ds_read_b128 v[56:59], v56 offset:48
	v_pk_fma_f32 v[34:35], v[34:35], s[2:3], v[36:37] op_sel_hi:[1,0,1]
	s_waitcnt lgkmcnt(3)
	v_fma_f32 v60, v44, v30, v0
	v_fmac_f32_e32 v60, v45, v32
	v_fmac_f32_e32 v60, v46, v26
	v_fmac_f32_e32 v60, v47, v28
	s_waitcnt lgkmcnt(2)
	v_fmac_f32_e32 v60, v48, v22
	v_fmac_f32_e32 v60, v49, v24
	v_fmac_f32_e32 v60, v50, v18
	v_fmac_f32_e32 v60, v51, v20
	s_waitcnt lgkmcnt(1)
	v_fmac_f32_e32 v60, v52, v16
	v_fmac_f32_e32 v60, v53, v14
	v_fmac_f32_e32 v60, v54, v10
	v_fma_f32 v61, v44, v31, v1
	v_fmac_f32_e32 v60, v55, v12
	v_fmac_f32_e32 v61, v45, v33
	s_waitcnt lgkmcnt(0)
	v_fmac_f32_e32 v60, v56, v8
	v_fmac_f32_e32 v61, v46, v27
	v_fmac_f32_e32 v60, v57, v6
	v_fmac_f32_e32 v61, v47, v29
	v_fmac_f32_e32 v60, v58, v4
	v_fmac_f32_e32 v61, v48, v23
	v_fmac_f32_e32 v60, v59, v2
	v_fmac_f32_e32 v61, v49, v25
	v_mul_f32_e64 v45, |v60|, s90
	v_fmac_f32_e32 v61, v50, v19
	v_exp_f32_e32 v45, v45
	v_fmac_f32_e32 v61, v51, v21
	v_fmac_f32_e32 v61, v52, v17
	v_fmac_f32_e32 v61, v53, v15
	v_fmac_f32_e32 v61, v54, v11
	v_add_f32_e32 v45, 1.0, v45
	v_fmac_f32_e32 v61, v55, v13
	v_cmp_gt_f32_e64 s[62:63], s92, v45
	v_fmac_f32_e32 v61, v56, v9
	v_fmac_f32_e32 v61, v57, v7
	v_cndmask_b32_e64 v46, 0, 32, s[62:63]
	v_ldexp_f32 v45, v45, v46
	v_fmac_f32_e32 v61, v58, v5
	v_log_f32_e32 v45, v45
	v_fmac_f32_e32 v61, v59, v3
	v_mul_f32_e64 v47, |v61|, s90
	v_exp_f32_e32 v47, v47
	v_mul_f32_e32 v46, 0x3f317217, v45
	v_fma_f32 v46, v45, s41, -v46
	v_fmac_f32_e32 v46, 0x3377d1cf, v45
	v_fmac_f32_e32 v46, 0x3f317217, v45
	v_cmp_lt_f32_e64 s[64:65], |v45|, s68
	v_add_f32_e32 v47, 1.0, v47
	v_min_f32_e32 v44, 0, v60
	v_cndmask_b32_e64 v45, v45, v46, s[64:65]
	v_cndmask_b32_e64 v46, 0, v187, s[62:63]
	v_cmp_gt_f32_e64 s[62:63], s92, v47
	v_sub_f32_e32 v46, v45, v46
	v_min_f32_e32 v45, 0, v61
	v_cndmask_b32_e64 v48, 0, 32, s[62:63]
	v_ldexp_f32 v47, v47, v48
	v_log_f32_e32 v47, v47
	s_nop 0
	v_mul_f32_e32 v48, 0x3f317217, v47
	v_fma_f32 v48, v47, s41, -v48
	v_fmac_f32_e32 v48, 0x3377d1cf, v47
	v_fmac_f32_e32 v48, 0x3f317217, v47
	v_cmp_lt_f32_e64 s[64:65], |v47|, s68
	s_nop 1
	v_cndmask_b32_e64 v47, v47, v48, s[64:65]
	v_cndmask_b32_e64 v48, 0, v187, s[62:63]
	v_sub_f32_e32 v47, v47, v48
	v_pk_add_f32 v[44:45], v[44:45], v[46:47] neg_lo:[0,1] neg_hi:[0,1]
	v_sub_u32_e32 v46, 63, v111
	v_cndmask_b32_e32 v46, v46, v111, vcc
	v_lshl_add_u32 v58, v46, 7, s10
	ds_read_b128 v[46:49], v58
	ds_read_b128 v[50:53], v58 offset:16
	ds_read_b128 v[54:57], v58 offset:32
	ds_read_b128 v[58:61], v58 offset:48
	s_waitcnt lgkmcnt(3)
	v_fma_f32 v62, v46, v30, v0
	v_fmac_f32_e32 v62, v47, v32
	v_fmac_f32_e32 v62, v48, v26
	v_fmac_f32_e32 v62, v49, v28
	s_waitcnt lgkmcnt(2)
	v_fmac_f32_e32 v62, v50, v22
	v_fmac_f32_e32 v62, v51, v24
	v_fmac_f32_e32 v62, v52, v18
	v_fmac_f32_e32 v62, v53, v20
	s_waitcnt lgkmcnt(1)
	v_fmac_f32_e32 v62, v54, v16
	v_fmac_f32_e32 v62, v55, v14
	v_fmac_f32_e32 v62, v56, v10
	v_fma_f32 v63, v46, v31, v1
	v_fmac_f32_e32 v62, v57, v12
	v_fmac_f32_e32 v63, v47, v33
	s_waitcnt lgkmcnt(0)
	v_fmac_f32_e32 v62, v58, v8
	v_fmac_f32_e32 v63, v48, v27
	v_fmac_f32_e32 v62, v59, v6
	v_fmac_f32_e32 v63, v49, v29
	v_fmac_f32_e32 v62, v60, v4
	v_fmac_f32_e32 v63, v50, v23
	v_fmac_f32_e32 v62, v61, v2
	v_fmac_f32_e32 v63, v51, v25
	v_mul_f32_e64 v47, |v62|, s90
	v_fmac_f32_e32 v63, v52, v19
	v_exp_f32_e32 v47, v47
	v_fmac_f32_e32 v63, v53, v21
	v_fmac_f32_e32 v63, v54, v17
	v_fmac_f32_e32 v63, v55, v15
	v_fmac_f32_e32 v63, v56, v11
	v_add_f32_e32 v47, 1.0, v47
	v_fmac_f32_e32 v63, v57, v13
	v_cmp_gt_f32_e64 s[62:63], s92, v47
	v_fmac_f32_e32 v63, v58, v9
	v_fmac_f32_e32 v63, v59, v7
	v_cndmask_b32_e64 v48, 0, 32, s[62:63]
	v_ldexp_f32 v47, v47, v48
	v_fmac_f32_e32 v63, v60, v5
	v_log_f32_e32 v47, v47
	v_fmac_f32_e32 v63, v61, v3
	v_mul_f32_e64 v49, |v63|, s90
	v_exp_f32_e32 v49, v49
	v_mul_f32_e32 v48, 0x3f317217, v47
	v_fma_f32 v48, v47, s41, -v48
	v_fmac_f32_e32 v48, 0x3377d1cf, v47
	v_fmac_f32_e32 v48, 0x3f317217, v47
	v_cmp_lt_f32_e64 s[64:65], |v47|, s68
	v_add_f32_e32 v49, 1.0, v49
	v_min_f32_e32 v46, 0, v62
	v_cndmask_b32_e64 v47, v47, v48, s[64:65]
	v_cndmask_b32_e64 v48, 0, v187, s[62:63]
	v_cmp_gt_f32_e64 s[62:63], s92, v49
	v_sub_f32_e32 v48, v47, v48
	v_min_f32_e32 v47, 0, v63
	v_cndmask_b32_e64 v50, 0, 32, s[62:63]
	v_ldexp_f32 v49, v49, v50
	v_log_f32_e32 v49, v49
	s_nop 0
	v_mul_f32_e32 v50, 0x3f317217, v49
	v_fma_f32 v50, v49, s41, -v50
	v_fmac_f32_e32 v50, 0x3377d1cf, v49
	v_fmac_f32_e32 v50, 0x3f317217, v49
	v_cmp_lt_f32_e64 s[64:65], |v49|, s68
	s_nop 1
	v_cndmask_b32_e64 v49, v49, v50, s[64:65]
	v_cndmask_b32_e64 v50, 0, v187, s[62:63]
	v_sub_f32_e32 v49, v49, v50
	v_pk_add_f32 v[46:47], v[46:47], v[48:49] neg_lo:[0,1] neg_hi:[0,1]
	v_sub_u32_e32 v48, 63, v108
	v_cndmask_b32_e32 v48, v48, v108, vcc
	v_lshl_add_u32 v60, v48, 7, s10
	ds_read_b128 v[48:51], v60
	ds_read_b128 v[52:55], v60 offset:16
	ds_read_b128 v[56:59], v60 offset:32
	ds_read_b128 v[60:63], v60 offset:48
	s_waitcnt lgkmcnt(3)
	v_fma_f32 v66, v48, v30, v0
	v_fmac_f32_e32 v66, v49, v32
	v_fmac_f32_e32 v66, v50, v26
	v_fmac_f32_e32 v66, v51, v28
	s_waitcnt lgkmcnt(2)
	v_fmac_f32_e32 v66, v52, v22
	v_fmac_f32_e32 v66, v53, v24
	v_fmac_f32_e32 v66, v54, v18
	v_fmac_f32_e32 v66, v55, v20
	s_waitcnt lgkmcnt(1)
	v_fmac_f32_e32 v66, v56, v16
	v_fmac_f32_e32 v66, v57, v14
	v_fmac_f32_e32 v66, v58, v10
	v_fma_f32 v67, v48, v31, v1
	v_fmac_f32_e32 v66, v59, v12
	v_fmac_f32_e32 v67, v49, v33
	s_waitcnt lgkmcnt(0)
	v_fmac_f32_e32 v66, v60, v8
	v_fmac_f32_e32 v67, v50, v27
	v_fmac_f32_e32 v66, v61, v6
	v_fmac_f32_e32 v67, v51, v29
	v_fmac_f32_e32 v66, v62, v4
	v_fmac_f32_e32 v67, v52, v23
	v_fmac_f32_e32 v66, v63, v2
	v_fmac_f32_e32 v67, v53, v25
	v_mul_f32_e64 v49, |v66|, s90
	v_fmac_f32_e32 v67, v54, v19
	v_exp_f32_e32 v49, v49
	v_fmac_f32_e32 v67, v55, v21
	v_fmac_f32_e32 v67, v56, v17
	v_fmac_f32_e32 v67, v57, v15
	v_fmac_f32_e32 v67, v58, v11
	v_add_f32_e32 v49, 1.0, v49
	v_fmac_f32_e32 v67, v59, v13
	v_cmp_gt_f32_e64 s[62:63], s92, v49
	v_fmac_f32_e32 v67, v60, v9
	v_fmac_f32_e32 v67, v61, v7
	v_cndmask_b32_e64 v50, 0, 32, s[62:63]
	v_ldexp_f32 v49, v49, v50
	v_fmac_f32_e32 v67, v62, v5
	v_log_f32_e32 v49, v49
	v_fmac_f32_e32 v67, v63, v3
	v_mul_f32_e64 v51, |v67|, s90
	v_exp_f32_e32 v51, v51
	v_mul_f32_e32 v50, 0x3f317217, v49
	v_fma_f32 v50, v49, s41, -v50
	v_fmac_f32_e32 v50, 0x3377d1cf, v49
	v_fmac_f32_e32 v50, 0x3f317217, v49
	v_cmp_lt_f32_e64 s[64:65], |v49|, s68
	v_add_f32_e32 v51, 1.0, v51
	v_min_f32_e32 v48, 0, v66
	v_cndmask_b32_e64 v49, v49, v50, s[64:65]
	v_cndmask_b32_e64 v50, 0, v187, s[62:63]
	v_cmp_gt_f32_e64 s[62:63], s92, v51
	v_sub_f32_e32 v50, v49, v50
	v_min_f32_e32 v49, 0, v67
	v_cndmask_b32_e64 v52, 0, 32, s[62:63]
	v_ldexp_f32 v51, v51, v52
	v_log_f32_e32 v51, v51
	s_nop 0
	v_mul_f32_e32 v52, 0x3f317217, v51
	v_fma_f32 v52, v51, s41, -v52
	v_fmac_f32_e32 v52, 0x3377d1cf, v51
	v_fmac_f32_e32 v52, 0x3f317217, v51
	v_cmp_lt_f32_e64 s[64:65], |v51|, s68
	s_nop 1
	v_cndmask_b32_e64 v51, v51, v52, s[64:65]
	v_cndmask_b32_e64 v52, 0, v187, s[62:63]
	v_sub_f32_e32 v51, v51, v52
	v_sub_u32_e32 v52, 63, v105
	v_cndmask_b32_e32 v52, v52, v105, vcc
	v_lshl_add_u32 v66, v52, 7, s10
	ds_read_b128 v[52:55], v66
	ds_read_b128 v[56:59], v66 offset:16
	ds_read_b128 v[60:63], v66 offset:32
	ds_read_b128 v[66:69], v66 offset:48
	s_waitcnt lgkmcnt(3)
	v_fma_f32 v70, v52, v30, v0
	v_fmac_f32_e32 v70, v53, v32
	v_fmac_f32_e32 v70, v54, v26
	v_fmac_f32_e32 v70, v55, v28
	s_waitcnt lgkmcnt(2)
	v_fmac_f32_e32 v70, v56, v22
	v_fmac_f32_e32 v70, v57, v24
	v_fmac_f32_e32 v70, v58, v18
	v_fmac_f32_e32 v70, v59, v20
	s_waitcnt lgkmcnt(1)
	v_fmac_f32_e32 v70, v60, v16
	v_fmac_f32_e32 v70, v61, v14
	v_fmac_f32_e32 v70, v62, v10
	v_fma_f32 v71, v52, v31, v1
	v_fmac_f32_e32 v70, v63, v12
	v_fmac_f32_e32 v71, v53, v33
	s_waitcnt lgkmcnt(0)
	v_fmac_f32_e32 v70, v66, v8
	v_fmac_f32_e32 v71, v54, v27
	v_fmac_f32_e32 v70, v67, v6
	v_fmac_f32_e32 v71, v55, v29
	v_fmac_f32_e32 v70, v68, v4
	v_fmac_f32_e32 v71, v56, v23
	v_fmac_f32_e32 v70, v69, v2
	v_fmac_f32_e32 v71, v57, v25
	v_mul_f32_e64 v53, |v70|, s90
	v_fmac_f32_e32 v71, v58, v19
	v_exp_f32_e32 v53, v53
	v_fmac_f32_e32 v71, v59, v21
	v_fmac_f32_e32 v71, v60, v17
	v_fmac_f32_e32 v71, v61, v15
	v_fmac_f32_e32 v71, v62, v11
	v_add_f32_e32 v53, 1.0, v53
	v_fmac_f32_e32 v71, v63, v13
	v_cmp_gt_f32_e64 s[62:63], s92, v53
	v_fmac_f32_e32 v71, v66, v9
	v_fmac_f32_e32 v71, v67, v7
	v_cndmask_b32_e64 v54, 0, 32, s[62:63]
	v_ldexp_f32 v53, v53, v54
	v_fmac_f32_e32 v71, v68, v5
	v_log_f32_e32 v53, v53
	v_fmac_f32_e32 v71, v69, v3
	v_mul_f32_e64 v55, |v71|, s90
	v_exp_f32_e32 v55, v55
	v_mul_f32_e32 v54, 0x3f317217, v53
	v_fma_f32 v54, v53, s41, -v54
	v_fmac_f32_e32 v54, 0x3377d1cf, v53
	v_fmac_f32_e32 v54, 0x3f317217, v53
	v_cmp_lt_f32_e64 s[64:65], |v53|, s68
	v_add_f32_e32 v55, 1.0, v55
	v_min_f32_e32 v52, 0, v70
	v_cndmask_b32_e64 v53, v53, v54, s[64:65]
	v_cndmask_b32_e64 v54, 0, v187, s[62:63]
	v_cmp_gt_f32_e64 s[62:63], s92, v55
	v_sub_f32_e32 v54, v53, v54
	v_min_f32_e32 v53, 0, v71
	v_cndmask_b32_e64 v56, 0, 32, s[62:63]
	v_ldexp_f32 v55, v55, v56
	v_log_f32_e32 v55, v55
	s_nop 0
	v_mul_f32_e32 v56, 0x3f317217, v55
	v_fma_f32 v56, v55, s41, -v56
	v_fmac_f32_e32 v56, 0x3377d1cf, v55
	v_fmac_f32_e32 v56, 0x3f317217, v55
	v_cmp_lt_f32_e64 s[64:65], |v55|, s68
	s_nop 1
	v_cndmask_b32_e64 v55, v55, v56, s[64:65]
	v_cndmask_b32_e64 v56, 0, v187, s[62:63]
	v_sub_f32_e32 v55, v55, v56
	v_sub_u32_e32 v56, 63, v101
	v_cndmask_b32_e32 v56, v56, v101, vcc
	v_lshl_add_u32 v70, v56, 7, s10
	ds_read_b128 v[56:59], v70
	ds_read_b128 v[60:63], v70 offset:16
	ds_read_b128 v[66:69], v70 offset:32
	ds_read_b128 v[70:73], v70 offset:48
	s_waitcnt lgkmcnt(3)
	v_fma_f32 v74, v56, v30, v0
	v_fmac_f32_e32 v74, v57, v32
	v_fmac_f32_e32 v74, v58, v26
	v_fmac_f32_e32 v74, v59, v28
	s_waitcnt lgkmcnt(2)
	v_fmac_f32_e32 v74, v60, v22
	v_fmac_f32_e32 v74, v61, v24
	v_fmac_f32_e32 v74, v62, v18
	v_fmac_f32_e32 v74, v63, v20
	s_waitcnt lgkmcnt(1)
	v_fmac_f32_e32 v74, v66, v16
	v_fmac_f32_e32 v74, v67, v14
	v_fmac_f32_e32 v74, v68, v10
	v_fma_f32 v75, v56, v31, v1
	v_fmac_f32_e32 v74, v69, v12
	v_fmac_f32_e32 v75, v57, v33
	s_waitcnt lgkmcnt(0)
	v_fmac_f32_e32 v74, v70, v8
	v_fmac_f32_e32 v75, v58, v27
	v_fmac_f32_e32 v74, v71, v6
	v_fmac_f32_e32 v75, v59, v29
	v_fmac_f32_e32 v74, v72, v4
	v_fmac_f32_e32 v75, v60, v23
	v_fmac_f32_e32 v74, v73, v2
	v_fmac_f32_e32 v75, v61, v25
	v_mul_f32_e64 v57, |v74|, s90
	v_fmac_f32_e32 v75, v62, v19
	v_exp_f32_e32 v57, v57
	v_fmac_f32_e32 v75, v63, v21
	v_fmac_f32_e32 v75, v66, v17
	v_fmac_f32_e32 v75, v67, v15
	v_fmac_f32_e32 v75, v68, v11
	v_add_f32_e32 v57, 1.0, v57
	v_fmac_f32_e32 v75, v69, v13
	v_cmp_gt_f32_e64 s[62:63], s92, v57
	v_fmac_f32_e32 v75, v70, v9
	v_fmac_f32_e32 v75, v71, v7
	v_cndmask_b32_e64 v58, 0, 32, s[62:63]
	v_ldexp_f32 v57, v57, v58
	v_fmac_f32_e32 v75, v72, v5
	v_log_f32_e32 v57, v57
	v_fmac_f32_e32 v75, v73, v3
	v_mul_f32_e64 v59, |v75|, s90
	v_exp_f32_e32 v59, v59
	v_mul_f32_e32 v58, 0x3f317217, v57
	v_fma_f32 v58, v57, s41, -v58
	v_fmac_f32_e32 v58, 0x3377d1cf, v57
	v_fmac_f32_e32 v58, 0x3f317217, v57
	v_cmp_lt_f32_e64 s[64:65], |v57|, s68
	v_add_f32_e32 v59, 1.0, v59
	v_min_f32_e32 v56, 0, v74
	v_cndmask_b32_e64 v57, v57, v58, s[64:65]
	v_cndmask_b32_e64 v58, 0, v187, s[62:63]
	v_cmp_gt_f32_e64 s[62:63], s92, v59
	v_sub_f32_e32 v58, v57, v58
	v_min_f32_e32 v57, 0, v75
	v_cndmask_b32_e64 v60, 0, 32, s[62:63]
	v_ldexp_f32 v59, v59, v60
	v_log_f32_e32 v59, v59
	s_nop 0
	v_mul_f32_e32 v60, 0x3f317217, v59
	v_fma_f32 v60, v59, s41, -v60
	v_fmac_f32_e32 v60, 0x3377d1cf, v59
	v_fmac_f32_e32 v60, 0x3f317217, v59
	v_cmp_lt_f32_e64 s[64:65], |v59|, s68
	s_nop 1
	v_cndmask_b32_e64 v59, v59, v60, s[64:65]
	v_cndmask_b32_e64 v60, 0, v187, s[62:63]
	v_sub_f32_e32 v59, v59, v60
	v_sub_u32_e32 v60, 63, v98
	v_cndmask_b32_e32 v60, v60, v98, vcc
	v_lshl_add_u32 v74, v60, 7, s10
	ds_read_b128 v[60:63], v74
	ds_read_b128 v[66:69], v74 offset:16
	ds_read_b128 v[70:73], v74 offset:32
	ds_read_b128 v[74:77], v74 offset:48
	s_waitcnt lgkmcnt(3)
	v_fma_f32 v78, v60, v30, v0
	v_fmac_f32_e32 v78, v61, v32
	v_fmac_f32_e32 v78, v62, v26
	v_fmac_f32_e32 v78, v63, v28
	s_waitcnt lgkmcnt(2)
	v_fmac_f32_e32 v78, v66, v22
	v_fmac_f32_e32 v78, v67, v24
	v_fmac_f32_e32 v78, v68, v18
	v_fmac_f32_e32 v78, v69, v20
	s_waitcnt lgkmcnt(1)
	v_fmac_f32_e32 v78, v70, v16
	v_fmac_f32_e32 v78, v71, v14
	v_fmac_f32_e32 v78, v72, v10
	v_fma_f32 v79, v60, v31, v1
	v_fmac_f32_e32 v78, v73, v12
	v_fmac_f32_e32 v79, v61, v33
	s_waitcnt lgkmcnt(0)
	v_fmac_f32_e32 v78, v74, v8
	v_fmac_f32_e32 v79, v62, v27
	v_fmac_f32_e32 v78, v75, v6
	v_fmac_f32_e32 v79, v63, v29
	v_fmac_f32_e32 v78, v76, v4
	v_fmac_f32_e32 v79, v66, v23
	v_fmac_f32_e32 v78, v77, v2
	v_fmac_f32_e32 v79, v67, v25
	v_mul_f32_e64 v61, |v78|, s90
	v_fmac_f32_e32 v79, v68, v19
	v_exp_f32_e32 v61, v61
	v_fmac_f32_e32 v79, v69, v21
	v_fmac_f32_e32 v79, v70, v17
	v_fmac_f32_e32 v79, v71, v15
	v_fmac_f32_e32 v79, v72, v11
	v_add_f32_e32 v61, 1.0, v61
	v_fmac_f32_e32 v79, v73, v13
	v_cmp_gt_f32_e64 s[62:63], s92, v61
	v_fmac_f32_e32 v79, v74, v9
	v_fmac_f32_e32 v79, v75, v7
	v_cndmask_b32_e64 v62, 0, 32, s[62:63]
	v_ldexp_f32 v61, v61, v62
	v_fmac_f32_e32 v79, v76, v5
	v_log_f32_e32 v61, v61
	v_fmac_f32_e32 v79, v77, v3
	v_mul_f32_e64 v63, |v79|, s90
	v_exp_f32_e32 v63, v63
	v_mul_f32_e32 v62, 0x3f317217, v61
	v_fma_f32 v62, v61, s41, -v62
	v_fmac_f32_e32 v62, 0x3377d1cf, v61
	v_fmac_f32_e32 v62, 0x3f317217, v61
	v_cmp_lt_f32_e64 s[64:65], |v61|, s68
	v_add_f32_e32 v63, 1.0, v63
	v_min_f32_e32 v60, 0, v78
	v_cndmask_b32_e64 v61, v61, v62, s[64:65]
	v_cndmask_b32_e64 v62, 0, v187, s[62:63]
	v_cmp_gt_f32_e64 s[62:63], s92, v63
	v_sub_f32_e32 v62, v61, v62
	v_min_f32_e32 v61, 0, v79
	v_cndmask_b32_e64 v66, 0, 32, s[62:63]
	v_ldexp_f32 v63, v63, v66
	v_log_f32_e32 v63, v63
	s_nop 0
	v_mul_f32_e32 v66, 0x3f317217, v63
	v_fma_f32 v66, v63, s41, -v66
	v_fmac_f32_e32 v66, 0x3377d1cf, v63
	v_fmac_f32_e32 v66, 0x3f317217, v63
	v_cmp_lt_f32_e64 s[64:65], |v63|, s68
	s_nop 1
	v_cndmask_b32_e64 v63, v63, v66, s[64:65]
	v_cndmask_b32_e64 v66, 0, v187, s[62:63]
	v_sub_f32_e32 v63, v63, v66
	v_sub_u32_e32 v66, 63, v95
	v_cndmask_b32_e32 v66, v66, v95, vcc
	v_lshl_add_u32 v78, v66, 7, s10
	ds_read_b128 v[66:69], v78
	ds_read_b128 v[70:73], v78 offset:16
	ds_read_b128 v[74:77], v78 offset:32
	ds_read_b128 v[78:81], v78 offset:48
	s_waitcnt lgkmcnt(3)
	v_fma_f32 v133, v66, v30, v0
	v_fmac_f32_e32 v133, v67, v32
	v_fmac_f32_e32 v133, v68, v26
	v_fmac_f32_e32 v133, v69, v28
	s_waitcnt lgkmcnt(2)
	v_fmac_f32_e32 v133, v70, v22
	v_fmac_f32_e32 v133, v71, v24
	v_fmac_f32_e32 v133, v72, v18
	v_fmac_f32_e32 v133, v73, v20
	s_waitcnt lgkmcnt(1)
	v_fmac_f32_e32 v133, v74, v16
	v_fmac_f32_e32 v133, v75, v14
	v_fmac_f32_e32 v133, v76, v10
	v_fma_f32 v134, v66, v31, v1
	v_fmac_f32_e32 v133, v77, v12
	v_fmac_f32_e32 v134, v67, v33
	s_waitcnt lgkmcnt(0)
	v_fmac_f32_e32 v133, v78, v8
	v_fmac_f32_e32 v134, v68, v27
	v_fmac_f32_e32 v133, v79, v6
	v_fmac_f32_e32 v134, v69, v29
	v_fmac_f32_e32 v133, v80, v4
	v_fmac_f32_e32 v134, v70, v23
	v_fmac_f32_e32 v133, v81, v2
	v_fmac_f32_e32 v134, v71, v25
	v_mul_f32_e64 v67, |v133|, s90
	v_fmac_f32_e32 v134, v72, v19
	v_exp_f32_e32 v67, v67
	v_fmac_f32_e32 v134, v73, v21
	v_fmac_f32_e32 v134, v74, v17
	v_fmac_f32_e32 v134, v75, v15
	v_fmac_f32_e32 v134, v76, v11
	v_add_f32_e32 v67, 1.0, v67
	v_fmac_f32_e32 v134, v77, v13
	v_cmp_gt_f32_e64 s[62:63], s92, v67
	v_fmac_f32_e32 v134, v78, v9
	v_fmac_f32_e32 v134, v79, v7
	v_cndmask_b32_e64 v68, 0, 32, s[62:63]
	v_ldexp_f32 v67, v67, v68
	v_fmac_f32_e32 v134, v80, v5
	v_log_f32_e32 v67, v67
	v_fmac_f32_e32 v134, v81, v3
	v_mul_f32_e64 v69, |v134|, s90
	v_exp_f32_e32 v69, v69
	v_mul_f32_e32 v68, 0x3f317217, v67
	v_fma_f32 v68, v67, s41, -v68
	v_fmac_f32_e32 v68, 0x3377d1cf, v67
	v_fmac_f32_e32 v68, 0x3f317217, v67
	v_cmp_lt_f32_e64 s[64:65], |v67|, s68
	v_add_f32_e32 v69, 1.0, v69
	v_min_f32_e32 v66, 0, v133
	v_cndmask_b32_e64 v67, v67, v68, s[64:65]
	v_cndmask_b32_e64 v68, 0, v187, s[62:63]
	v_cmp_gt_f32_e64 s[62:63], s92, v69
	v_sub_f32_e32 v68, v67, v68
	v_min_f32_e32 v67, 0, v134
	v_cndmask_b32_e64 v70, 0, 32, s[62:63]
	v_ldexp_f32 v69, v69, v70
	v_log_f32_e32 v69, v69
	s_nop 0
	v_mul_f32_e32 v70, 0x3f317217, v69
	v_fma_f32 v70, v69, s41, -v70
	v_fmac_f32_e32 v70, 0x3377d1cf, v69
	v_fmac_f32_e32 v70, 0x3f317217, v69
	v_cmp_lt_f32_e64 s[64:65], |v69|, s68
	s_nop 1
	v_cndmask_b32_e64 v69, v69, v70, s[64:65]
	v_cndmask_b32_e64 v70, 0, v187, s[62:63]
	v_sub_f32_e32 v69, v69, v70
	v_sub_u32_e32 v70, 63, v92
	v_cndmask_b32_e32 v70, v70, v92, vcc
	v_lshl_add_u32 v133, v70, 7, s10
	ds_read_b128 v[70:73], v133
	ds_read_b128 v[74:77], v133 offset:16
	ds_read_b128 v[78:81], v133 offset:32
	ds_read_b128 v[134:137], v133 offset:48
	s_waitcnt lgkmcnt(3)
	v_fma_f32 v133, v70, v30, v0
	v_fmac_f32_e32 v133, v71, v32
	v_fmac_f32_e32 v133, v72, v26
	v_fmac_f32_e32 v133, v73, v28
	s_waitcnt lgkmcnt(2)
	v_fmac_f32_e32 v133, v74, v22
	v_fmac_f32_e32 v133, v75, v24
	v_fmac_f32_e32 v133, v76, v18
	v_fmac_f32_e32 v133, v77, v20
	s_waitcnt lgkmcnt(1)
	v_fmac_f32_e32 v133, v78, v16
	v_fmac_f32_e32 v133, v79, v14
	v_fmac_f32_e32 v133, v80, v10
	v_fma_f32 v138, v70, v31, v1
	v_fmac_f32_e32 v133, v81, v12
	v_fmac_f32_e32 v138, v71, v33
	s_waitcnt lgkmcnt(0)
	v_fmac_f32_e32 v133, v134, v8
	v_fmac_f32_e32 v138, v72, v27
	v_fmac_f32_e32 v133, v135, v6
	v_fmac_f32_e32 v138, v73, v29
	v_fmac_f32_e32 v133, v136, v4
	v_fmac_f32_e32 v138, v74, v23
	v_fmac_f32_e32 v133, v137, v2
	v_fmac_f32_e32 v138, v75, v25
	v_mul_f32_e64 v71, |v133|, s90
	v_fmac_f32_e32 v138, v76, v19
	v_exp_f32_e32 v71, v71
	v_fmac_f32_e32 v138, v77, v21
	v_fmac_f32_e32 v138, v78, v17
	v_fmac_f32_e32 v138, v79, v15
	v_fmac_f32_e32 v138, v80, v11
	v_add_f32_e32 v71, 1.0, v71
	v_fmac_f32_e32 v138, v81, v13
	v_cmp_gt_f32_e64 s[62:63], s92, v71
	v_fmac_f32_e32 v138, v134, v9
	v_fmac_f32_e32 v138, v135, v7
	v_cndmask_b32_e64 v72, 0, 32, s[62:63]
	v_ldexp_f32 v71, v71, v72
	v_fmac_f32_e32 v138, v136, v5
	v_log_f32_e32 v71, v71
	v_fmac_f32_e32 v138, v137, v3
	v_mul_f32_e64 v73, |v138|, s90
	v_exp_f32_e32 v73, v73
	v_mul_f32_e32 v72, 0x3f317217, v71
	v_fma_f32 v72, v71, s41, -v72
	v_fmac_f32_e32 v72, 0x3377d1cf, v71
	v_fmac_f32_e32 v72, 0x3f317217, v71
	v_cmp_lt_f32_e64 s[64:65], |v71|, s68
	v_add_f32_e32 v73, 1.0, v73
	v_min_f32_e32 v70, 0, v133
	v_cndmask_b32_e64 v71, v71, v72, s[64:65]
	v_cndmask_b32_e64 v72, 0, v187, s[62:63]
	v_cmp_gt_f32_e64 s[62:63], s92, v73
	v_sub_f32_e32 v72, v71, v72
	v_min_f32_e32 v71, 0, v138
	v_cndmask_b32_e64 v74, 0, 32, s[62:63]
	v_ldexp_f32 v73, v73, v74
	v_log_f32_e32 v73, v73
	s_nop 0
	v_mul_f32_e32 v74, 0x3f317217, v73
	v_fma_f32 v74, v73, s41, -v74
	v_fmac_f32_e32 v74, 0x3377d1cf, v73
	v_fmac_f32_e32 v74, 0x3f317217, v73
	v_cmp_lt_f32_e64 s[64:65], |v73|, s68
	s_nop 1
	v_cndmask_b32_e64 v73, v73, v74, s[64:65]
	v_cndmask_b32_e64 v74, 0, v187, s[62:63]
	v_sub_f32_e32 v73, v73, v74
	v_sub_u32_e32 v74, 63, v89
	v_cndmask_b32_e32 v74, v74, v89, vcc
	v_lshl_add_u32 v133, v74, 7, s10
	ds_read_b128 v[74:77], v133
	ds_read_b128 v[78:81], v133 offset:16
	ds_read_b128 v[134:137], v133 offset:32
	ds_read_b128 v[138:141], v133 offset:48
	s_waitcnt lgkmcnt(3)
	v_fma_f32 v133, v74, v30, v0
	v_fmac_f32_e32 v133, v75, v32
	v_fmac_f32_e32 v133, v76, v26
	v_fmac_f32_e32 v133, v77, v28
	s_waitcnt lgkmcnt(2)
	v_fmac_f32_e32 v133, v78, v22
	v_fmac_f32_e32 v133, v79, v24
	v_fmac_f32_e32 v133, v80, v18
	v_fmac_f32_e32 v133, v81, v20
	s_waitcnt lgkmcnt(1)
	v_fmac_f32_e32 v133, v134, v16
	v_fmac_f32_e32 v133, v135, v14
	v_fmac_f32_e32 v133, v136, v10
	v_fma_f32 v142, v74, v31, v1
	v_fmac_f32_e32 v133, v137, v12
	v_fmac_f32_e32 v142, v75, v33
	s_waitcnt lgkmcnt(0)
	v_fmac_f32_e32 v133, v138, v8
	v_fmac_f32_e32 v142, v76, v27
	v_fmac_f32_e32 v133, v139, v6
	v_fmac_f32_e32 v142, v77, v29
	v_fmac_f32_e32 v133, v140, v4
	v_fmac_f32_e32 v142, v78, v23
	v_fmac_f32_e32 v133, v141, v2
	v_fmac_f32_e32 v142, v79, v25
	v_mul_f32_e64 v75, |v133|, s90
	v_fmac_f32_e32 v142, v80, v19
	v_exp_f32_e32 v75, v75
	v_fmac_f32_e32 v142, v81, v21
	v_fmac_f32_e32 v142, v134, v17
	v_fmac_f32_e32 v142, v135, v15
	v_fmac_f32_e32 v142, v136, v11
	v_add_f32_e32 v75, 1.0, v75
	v_fmac_f32_e32 v142, v137, v13
	v_cmp_gt_f32_e64 s[62:63], s92, v75
	v_fmac_f32_e32 v142, v138, v9
	v_fmac_f32_e32 v142, v139, v7
	v_cndmask_b32_e64 v76, 0, 32, s[62:63]
	v_ldexp_f32 v75, v75, v76
	v_fmac_f32_e32 v142, v140, v5
	v_log_f32_e32 v75, v75
	v_fmac_f32_e32 v142, v141, v3
	v_mul_f32_e64 v77, |v142|, s90
	v_exp_f32_e32 v77, v77
	v_mul_f32_e32 v76, 0x3f317217, v75
	v_fma_f32 v76, v75, s41, -v76
	v_fmac_f32_e32 v76, 0x3377d1cf, v75
	v_fmac_f32_e32 v76, 0x3f317217, v75
	v_cmp_lt_f32_e64 s[64:65], |v75|, s68
	v_add_f32_e32 v77, 1.0, v77
	v_min_f32_e32 v74, 0, v133
	v_cndmask_b32_e64 v75, v75, v76, s[64:65]
	v_cndmask_b32_e64 v76, 0, v187, s[62:63]
	v_cmp_gt_f32_e64 s[62:63], s92, v77
	v_sub_f32_e32 v76, v75, v76
	v_min_f32_e32 v75, 0, v142
	v_cndmask_b32_e64 v78, 0, 32, s[62:63]
	v_ldexp_f32 v77, v77, v78
	v_log_f32_e32 v77, v77
	s_nop 0
	v_mul_f32_e32 v78, 0x3f317217, v77
	v_fma_f32 v78, v77, s41, -v78
	v_fmac_f32_e32 v78, 0x3377d1cf, v77
	v_fmac_f32_e32 v78, 0x3f317217, v77
	v_cmp_lt_f32_e64 s[64:65], |v77|, s68
	s_nop 1
	v_cndmask_b32_e64 v77, v77, v78, s[64:65]
	v_cndmask_b32_e64 v78, 0, v187, s[62:63]
	v_sub_f32_e32 v77, v77, v78
	v_sub_u32_e32 v78, 63, v86
	v_cndmask_b32_e32 v78, v78, v86, vcc
	v_lshl_add_u32 v133, v78, 7, s10
	ds_read_b128 v[78:81], v133
	ds_read_b128 v[134:137], v133 offset:16
	ds_read_b128 v[138:141], v133 offset:32
	ds_read_b128 v[142:145], v133 offset:48
	s_waitcnt lgkmcnt(3)
	v_fma_f32 v133, v78, v30, v0
	v_fmac_f32_e32 v133, v79, v32
	v_fmac_f32_e32 v133, v80, v26
	v_fmac_f32_e32 v133, v81, v28
	s_waitcnt lgkmcnt(2)
	v_fmac_f32_e32 v133, v134, v22
	v_fmac_f32_e32 v133, v135, v24
	v_fmac_f32_e32 v133, v136, v18
	v_fmac_f32_e32 v133, v137, v20
	s_waitcnt lgkmcnt(1)
	v_fmac_f32_e32 v133, v138, v16
	v_fmac_f32_e32 v133, v139, v14
	v_fmac_f32_e32 v133, v140, v10
	v_fma_f32 v146, v78, v31, v1
	v_fmac_f32_e32 v133, v141, v12
	v_fmac_f32_e32 v146, v79, v33
	s_waitcnt lgkmcnt(0)
	v_fmac_f32_e32 v133, v142, v8
	v_fmac_f32_e32 v146, v80, v27
	v_fmac_f32_e32 v133, v143, v6
	v_fmac_f32_e32 v146, v81, v29
	v_fmac_f32_e32 v133, v144, v4
	v_fmac_f32_e32 v146, v134, v23
	v_fmac_f32_e32 v133, v145, v2
	v_fmac_f32_e32 v146, v135, v25
	v_mul_f32_e64 v79, |v133|, s90
	v_fmac_f32_e32 v146, v136, v19
	v_exp_f32_e32 v79, v79
	v_fmac_f32_e32 v146, v137, v21
	v_fmac_f32_e32 v146, v138, v17
	v_fmac_f32_e32 v146, v139, v15
	v_fmac_f32_e32 v146, v140, v11
	v_add_f32_e32 v79, 1.0, v79
	v_fmac_f32_e32 v146, v141, v13
	v_cmp_gt_f32_e64 s[62:63], s92, v79
	v_fmac_f32_e32 v146, v142, v9
	v_fmac_f32_e32 v146, v143, v7
	v_cndmask_b32_e64 v80, 0, 32, s[62:63]
	v_ldexp_f32 v79, v79, v80
	v_fmac_f32_e32 v146, v144, v5
	v_log_f32_e32 v79, v79
	v_fmac_f32_e32 v146, v145, v3
	v_mul_f32_e64 v81, |v146|, s90
	v_exp_f32_e32 v81, v81
	v_mul_f32_e32 v80, 0x3f317217, v79
	v_fma_f32 v80, v79, s41, -v80
	v_fmac_f32_e32 v80, 0x3377d1cf, v79
	v_fmac_f32_e32 v80, 0x3f317217, v79
	v_cmp_lt_f32_e64 s[64:65], |v79|, s68
	v_add_f32_e32 v81, 1.0, v81
	v_min_f32_e32 v78, 0, v133
	v_cndmask_b32_e64 v79, v79, v80, s[64:65]
	v_cndmask_b32_e64 v80, 0, v187, s[62:63]
	v_cmp_gt_f32_e64 s[62:63], s92, v81
	v_sub_f32_e32 v80, v79, v80
	v_min_f32_e32 v79, 0, v146
	v_cndmask_b32_e64 v133, 0, 32, s[62:63]
	v_ldexp_f32 v81, v81, v133
	v_log_f32_e32 v81, v81
	s_nop 0
	v_mul_f32_e32 v133, 0x3f317217, v81
	v_fma_f32 v133, v81, s41, -v133
	v_fmac_f32_e32 v133, 0x3377d1cf, v81
	v_fmac_f32_e32 v133, 0x3f317217, v81
	v_cmp_lt_f32_e64 s[64:65], |v81|, s68
	s_nop 1
	v_cndmask_b32_e64 v81, v81, v133, s[64:65]
	v_cndmask_b32_e64 v133, 0, v187, s[62:63]
	v_sub_f32_e32 v81, v81, v133
	v_sub_u32_e32 v133, 63, v83
	v_cndmask_b32_e32 v133, v133, v83, vcc
	v_lshl_add_u32 v133, v133, 7, s10
	ds_read_b128 v[134:137], v133
	ds_read_b128 v[138:141], v133 offset:16
	ds_read_b128 v[142:145], v133 offset:32
	ds_read_b128 v[154:157], v133 offset:48
	s_or_b32 s10, s12, s0
	s_waitcnt lgkmcnt(3)
	v_fma_f32 v0, v134, v30, v0
	v_fmac_f32_e32 v0, v135, v32
	v_fmac_f32_e32 v0, v136, v26
	v_fmac_f32_e32 v0, v137, v28
	s_waitcnt lgkmcnt(2)
	v_fmac_f32_e32 v0, v138, v22
	v_fmac_f32_e32 v0, v139, v24
	v_fmac_f32_e32 v0, v140, v18
	v_fmac_f32_e32 v0, v141, v20
	v_fmac_f32_e32 v1, v134, v31
	s_waitcnt lgkmcnt(1)
	v_fmac_f32_e32 v0, v142, v16
	v_fmac_f32_e32 v1, v135, v33
	v_fmac_f32_e32 v0, v143, v14
	v_fmac_f32_e32 v1, v136, v27
	v_fmac_f32_e32 v0, v144, v10
	v_fmac_f32_e32 v1, v137, v29
	v_fmac_f32_e32 v0, v145, v12
	v_fmac_f32_e32 v1, v138, v23
	s_waitcnt lgkmcnt(0)
	v_fmac_f32_e32 v0, v154, v8
	v_fmac_f32_e32 v1, v139, v25
	v_fmac_f32_e32 v0, v155, v6
	v_fmac_f32_e32 v1, v140, v19
	v_fmac_f32_e32 v0, v156, v4
	v_fmac_f32_e32 v1, v141, v21
	v_fmac_f32_e32 v0, v157, v2
	v_fmac_f32_e32 v1, v142, v17
	v_min_f32_e32 v2, 0, v0
	v_mul_f32_e64 v0, |v0|, s90
	v_fmac_f32_e32 v1, v143, v15
	v_exp_f32_e32 v0, v0
	v_fmac_f32_e32 v1, v144, v11
	v_fmac_f32_e32 v1, v145, v13
	v_fmac_f32_e32 v1, v154, v9
	v_fmac_f32_e32 v1, v155, v7
	v_add_f32_e32 v0, 1.0, v0
	v_fmac_f32_e32 v1, v156, v5
	v_cmp_gt_f32_e32 vcc, s92, v0
	v_fmac_f32_e32 v1, v157, v3
	v_pk_fma_f32 v[32:33], v[44:45], s[2:3], v[34:35] op_sel_hi:[1,0,1]
	v_cndmask_b32_e64 v3, 0, 32, vcc
	v_ldexp_f32 v0, v0, v3
	v_log_f32_e32 v0, v0
	v_pk_fma_f32 v[30:31], v[46:47], s[2:3], v[32:33] op_sel_hi:[1,0,1]
	v_add_u32_e32 v44, 0, v64
	s_ashr_i32 s11, s10, 31
	v_mul_f32_e32 v3, 0x3f317217, v0
	v_fma_f32 v3, v0, s41, -v3
	v_fmac_f32_e32 v3, 0x3377d1cf, v0
	v_fmac_f32_e32 v3, 0x3f317217, v0
	v_cmp_lt_f32_e64 s[62:63], |v0|, s68
	v_lshlrev_b32_e32 v45, 2, v127
	v_add_u32_e32 v18, 0, v45
	v_cndmask_b32_e64 v0, v0, v3, s[62:63]
	v_cndmask_b32_e32 v3, 0, v187, vcc
	v_sub_f32_e32 v0, v0, v3
	v_min_f32_e32 v3, 0, v1
	v_mul_f32_e64 v1, |v1|, s90
	v_exp_f32_e32 v1, v1
	s_movk_i32 s0, 0x2100
	v_add_f32_e32 v1, 1.0, v1
	v_cmp_gt_f32_e32 vcc, s92, v1
	s_nop 1
	v_cndmask_b32_e64 v4, 0, 32, vcc
	v_ldexp_f32 v1, v1, v4
	v_log_f32_e32 v1, v1
	s_nop 0
	v_mul_f32_e32 v4, 0x3f317217, v1
	v_fma_f32 v4, v1, s41, -v4
	v_fmac_f32_e32 v4, 0x3377d1cf, v1
	v_fmac_f32_e32 v4, 0x3f317217, v1
	v_cmp_lt_f32_e64 s[62:63], |v1|, s68
	s_nop 1
	v_cndmask_b32_e64 v1, v1, v4, s[62:63]
	v_cndmask_b32_e32 v4, 0, v187, vcc
	v_sub_f32_e32 v1, v1, v4
	v_pk_add_f32 v[4:5], v[48:49], v[50:51] neg_lo:[0,1] neg_hi:[0,1]
	v_pk_add_f32 v[0:1], v[2:3], v[0:1] neg_lo:[0,1] neg_hi:[0,1]
	v_pk_fma_f32 v[28:29], v[4:5], s[2:3], v[30:31] op_sel_hi:[1,0,1]
	v_pk_add_f32 v[4:5], v[52:53], v[54:55] neg_lo:[0,1] neg_hi:[0,1]
	v_cmp_lt_i32_e32 vcc, 0, v123
	v_pk_fma_f32 v[26:27], v[4:5], s[2:3], v[28:29] op_sel_hi:[1,0,1]
	v_pk_add_f32 v[4:5], v[56:57], v[58:59] neg_lo:[0,1] neg_hi:[0,1]
	v_lshlrev_b32_e32 v50, 7, v127
	v_pk_fma_f32 v[24:25], v[4:5], s[2:3], v[26:27] op_sel_hi:[1,0,1]
	v_pk_add_f32 v[4:5], v[60:61], v[62:63] neg_lo:[0,1] neg_hi:[0,1]
	s_nop 0
	v_pk_fma_f32 v[22:23], v[4:5], s[2:3], v[24:25] op_sel_hi:[1,0,1]
	v_pk_add_f32 v[4:5], v[66:67], v[68:69] neg_lo:[0,1] neg_hi:[0,1]
	s_nop 0
	v_pk_fma_f32 v[20:21], v[4:5], s[2:3], v[22:23] op_sel_hi:[1,0,1]
	v_pk_add_f32 v[4:5], v[70:71], v[72:73] neg_lo:[0,1] neg_hi:[0,1]
	s_nop 0
	v_pk_fma_f32 v[16:17], v[4:5], s[2:3], v[20:21] op_sel_hi:[1,0,1]
	v_pk_add_f32 v[4:5], v[74:75], v[76:77] neg_lo:[0,1] neg_hi:[0,1]
	s_nop 0
	v_pk_fma_f32 v[14:15], v[4:5], s[2:3], v[16:17] op_sel_hi:[1,0,1]
	v_pk_add_f32 v[4:5], v[78:79], v[80:81] neg_lo:[0,1] neg_hi:[0,1]
	s_nop 0
	v_pk_fma_f32 v[10:11], v[4:5], s[2:3], v[14:15] op_sel_hi:[1,0,1]
	s_nop 0
	v_pk_fma_f32 v[2:3], v[0:1], s[2:3], v[10:11] op_sel_hi:[1,0,1]
	v_add_u32_e32 v0, 0x21400, v44
	v_lshl_add_u32 v1, v123, 10, v0
	ds_write_b64 v1, v[2:3]
	s_waitcnt lgkmcnt(0)
	s_barrier
	ds_read2st64_b64 v[6:9], v0 offset1:2
	ds_read2st64_b64 v[46:49], v0 offset0:4 offset1:6
	s_lshl_b64 s[2:3], s[10:11], 15
	s_add_u32 s12, s23, s2
	s_addc_u32 s13, s6, s3
	s_waitcnt lgkmcnt(1)
	v_pk_add_f32 v[4:5], v[6:7], v[8:9]
	v_pk_add_f32 v[6:7], v[6:7], 0 op_sel_hi:[1,0]
	s_waitcnt lgkmcnt(0)
	v_pk_add_f32 v[0:1], v[4:5], v[46:47]
	v_cndmask_b32_e32 v7, 0, v7, vcc
	v_cndmask_b32_e32 v6, 0, v6, vcc
	v_cmp_lt_i32_e32 vcc, 1, v123
	v_pk_add_f32 v[8:9], v[8:9], v[6:7]
	v_pk_add_f32 v[0:1], v[0:1], v[48:49]
	v_cndmask_b32_e32 v7, v7, v9, vcc
	v_cndmask_b32_e32 v6, v6, v8, vcc
	v_cmp_lt_i32_e32 vcc, 2, v123
	v_pk_add_f32 v[8:9], v[46:47], v[6:7]
	v_lshlrev_b32_e32 v48, 16, v132
	v_cndmask_b32_e32 v13, v7, v9, vcc
	v_cndmask_b32_e32 v12, v6, v8, vcc
	v_pk_add_f32 v[42:43], v[42:43], v[12:13]
	v_mul_f32_e32 v6, 0x3fb8aa3b, v4
	v_pk_add_f32 v[46:47], v[42:43], v[4:5] neg_lo:[0,1] neg_hi:[0,1]
	v_pk_add_f32 v[42:43], v[4:5], v[42:43] neg_lo:[0,1] neg_hi:[0,1]
	v_mul_f32_e32 v19, 0x3fb8aa3b, v46
	v_exp_f32_e32 v46, v19
	v_mul_f32_e32 v19, 0x3fb8aa3b, v47
	v_exp_f32_e32 v47, v19
	v_mul_f32_e32 v19, 0x3fb8aa3b, v42
	v_exp_f32_e32 v42, v19
	v_mul_f32_e32 v19, 0x3fb8aa3b, v43
	v_exp_f32_e32 v8, v6
	v_mul_f32_e32 v6, 0x3fb8aa3b, v5
	v_exp_f32_e32 v43, v19
	v_exp_f32_e32 v9, v6
	v_pk_add_f32 v[6:7], v[0:1], v[4:5] neg_lo:[0,1] neg_hi:[0,1]
	v_and_b32_e32 v49, 0xffff0000, v132
	v_mul_f32_e32 v6, 0x3fb8aa3b, v6
	v_mul_f32_e32 v7, 0x3fb8aa3b, v7
	v_pk_mul_f32 v[46:47], v[46:47], v[48:49]
	v_exp_f32_e32 v6, v6
	v_exp_f32_e32 v7, v7
	s_add_u32 s14, s7, s2
	v_lshlrev_b32_e32 v48, 16, v131
	v_and_b32_e32 v49, 0xffff0000, v131
	v_cvt_pk_bf16_f32 v19, v46, v47
	s_addc_u32 s15, s58, s3
	v_pk_mul_f32 v[42:43], v[42:43], v[48:49]
	v_mad_u64_u32 v[48:49], s[2:3], v123, s0, v[18:19]
	v_cvt_pk_bf16_f32 v49, v42, v43
	v_pk_mul_f32 v[46:47], v[8:9], v[46:47]
	ds_write2st64_b32 v48, v19, v49 offset1:132
	v_cvt_pk_bf16_f32 v19, v46, v47
	v_lshl_or_b32 v46, v123, 13, v45
	v_ashrrev_i32_e32 v47, 31, v46
	v_pk_mul_f32 v[42:43], v[6:7], v[42:43]
	v_pk_add_f32 v[40:41], v[40:41], v[12:13]
	v_lshl_add_u64 v[46:47], s[12:13], 0, v[46:47]
	v_cvt_pk_bf16_f32 v48, v42, v43
	v_pk_add_f32 v[42:43], v[40:41], v[4:5] neg_lo:[0,1] neg_hi:[0,1]
	global_store_dword v[46:47], v19, off
	v_mul_f32_e32 v19, 0x3fb8aa3b, v42
	v_exp_f32_e32 v42, v19
	v_mul_f32_e32 v19, 0x3fb8aa3b, v43
	v_pk_add_f32 v[40:41], v[4:5], v[40:41] neg_lo:[0,1] neg_hi:[0,1]
	v_exp_f32_e32 v43, v19
	v_mul_f32_e32 v19, 0x3fb8aa3b, v40
	v_exp_f32_e32 v40, v19
	v_mul_f32_e32 v19, 0x3fb8aa3b, v41
	v_exp_f32_e32 v41, v19
	v_lshlrev_b32_e32 v46, 16, v130
	v_and_b32_e32 v47, 0xffff0000, v130
	v_pk_mul_f32 v[42:43], v[42:43], v[46:47]
	v_lshlrev_b32_e32 v46, 16, v129
	v_and_b32_e32 v47, 0xffff0000, v129
	v_pk_mul_f32 v[40:41], v[40:41], v[46:47]
	v_cvt_pk_bf16_f32 v46, v42, v43
	v_pk_mul_f32 v[42:43], v[8:9], v[42:43]
	v_mad_u64_u32 v[18:19], s[2:3], v128, s37, v[18:19]
	v_cvt_pk_bf16_f32 v47, v42, v43
	v_lshl_or_b32 v42, v128, 9, v45
	v_ashrrev_i32_e32 v43, 31, v42
	v_cvt_pk_bf16_f32 v19, v40, v41
	v_lshl_add_u64 v[42:43], s[12:13], 0, v[42:43]
	v_pk_mul_f32 v[40:41], v[6:7], v[40:41]
	v_pk_add_f32 v[38:39], v[38:39], v[12:13]
	global_store_dword v[42:43], v47, off
	v_cvt_pk_bf16_f32 v47, v40, v41
	v_pk_add_f32 v[40:41], v[38:39], v[4:5] neg_lo:[0,1] neg_hi:[0,1]
	v_pk_add_f32 v[38:39], v[4:5], v[38:39] neg_lo:[0,1] neg_hi:[0,1]
	v_mul_f32_e32 v40, 0x3fb8aa3b, v40
	v_mul_f32_e32 v41, 0x3fb8aa3b, v41
	v_exp_f32_e32 v40, v40
	v_exp_f32_e32 v41, v41
	v_mul_f32_e32 v38, 0x3fb8aa3b, v38
	v_mul_f32_e32 v39, 0x3fb8aa3b, v39
	v_exp_f32_e32 v38, v38
	v_exp_f32_e32 v39, v39
	v_lshlrev_b32_e32 v42, 16, v126
	v_and_b32_e32 v43, 0xffff0000, v126
	v_pk_mul_f32 v[40:41], v[40:41], v[42:43]
	v_lshlrev_b32_e32 v42, 16, v125
	v_and_b32_e32 v43, 0xffff0000, v125
	v_pk_mul_f32 v[38:39], v[38:39], v[42:43]
	v_cvt_pk_bf16_f32 v42, v40, v41
	ds_write2_b32 v18, v46, v42 offset1:132
	v_cvt_pk_bf16_f32 v42, v38, v39
	v_add_u32_e32 v43, 0x8400, v18
	v_pk_mul_f32 v[40:41], v[8:9], v[40:41]
	ds_write2_b32 v43, v19, v42 offset1:132
	v_cvt_pk_bf16_f32 v19, v40, v41
	v_lshl_or_b32 v40, v124, 9, v45
	v_ashrrev_i32_e32 v41, 31, v40
	v_lshl_add_u64 v[40:41], s[12:13], 0, v[40:41]
	v_pk_mul_f32 v[38:39], v[6:7], v[38:39]
	v_pk_add_f32 v[36:37], v[36:37], v[12:13]
	global_store_dword v[40:41], v19, off
	v_cvt_pk_bf16_f32 v19, v38, v39
	v_pk_add_f32 v[38:39], v[36:37], v[4:5] neg_lo:[0,1] neg_hi:[0,1]
	v_pk_add_f32 v[36:37], v[4:5], v[36:37] neg_lo:[0,1] neg_hi:[0,1]
	v_mul_f32_e32 v38, 0x3fb8aa3b, v38
	v_mul_f32_e32 v39, 0x3fb8aa3b, v39
	v_exp_f32_e32 v38, v38
	v_exp_f32_e32 v39, v39
	v_mul_f32_e32 v36, 0x3fb8aa3b, v36
	v_mul_f32_e32 v37, 0x3fb8aa3b, v37
	v_exp_f32_e32 v36, v36
	v_exp_f32_e32 v37, v37
	v_lshlrev_b32_e32 v40, 16, v122
	v_and_b32_e32 v41, 0xffff0000, v122
	v_pk_mul_f32 v[38:39], v[38:39], v[40:41]
	v_lshlrev_b32_e32 v40, 16, v121
	v_and_b32_e32 v41, 0xffff0000, v121
	v_pk_mul_f32 v[36:37], v[36:37], v[40:41]
	v_cvt_pk_bf16_f32 v40, v38, v39
	v_pk_mul_f32 v[38:39], v[8:9], v[38:39]
	v_cvt_pk_bf16_f32 v41, v36, v37
	v_cvt_pk_bf16_f32 v42, v38, v39
	v_lshl_or_b32 v38, v120, 9, v45
	v_ashrrev_i32_e32 v39, 31, v38
	v_lshl_add_u64 v[38:39], s[12:13], 0, v[38:39]
	v_pk_mul_f32 v[36:37], v[6:7], v[36:37]
	v_pk_add_f32 v[34:35], v[34:35], v[12:13]
	global_store_dword v[38:39], v42, off
	v_cvt_pk_bf16_f32 v42, v36, v37
	v_pk_add_f32 v[36:37], v[34:35], v[4:5] neg_lo:[0,1] neg_hi:[0,1]
	v_pk_add_f32 v[34:35], v[4:5], v[34:35] neg_lo:[0,1] neg_hi:[0,1]
	v_mul_f32_e32 v36, 0x3fb8aa3b, v36
	v_mul_f32_e32 v37, 0x3fb8aa3b, v37
	v_exp_f32_e32 v36, v36
	v_exp_f32_e32 v37, v37
	v_mul_f32_e32 v34, 0x3fb8aa3b, v34
	v_mul_f32_e32 v35, 0x3fb8aa3b, v35
	v_exp_f32_e32 v34, v34
	v_exp_f32_e32 v35, v35
	v_lshlrev_b32_e32 v38, 16, v119
	v_and_b32_e32 v39, 0xffff0000, v119
	v_pk_mul_f32 v[36:37], v[36:37], v[38:39]
	v_lshlrev_b32_e32 v38, 16, v118
	v_and_b32_e32 v39, 0xffff0000, v118
	v_pk_mul_f32 v[34:35], v[34:35], v[38:39]
	v_cvt_pk_bf16_f32 v38, v36, v37
	v_add_u32_e32 v39, 0x400, v18
	ds_write2_b32 v39, v40, v38 offset0:8 offset1:140
	v_cvt_pk_bf16_f32 v38, v34, v35
	v_add_u32_e32 v39, 0x8800, v18
	v_pk_mul_f32 v[36:37], v[8:9], v[36:37]
	ds_write2_b32 v39, v41, v38 offset0:8 offset1:140
	v_cvt_pk_bf16_f32 v38, v36, v37
	v_lshl_or_b32 v36, v117, 9, v45
	v_ashrrev_i32_e32 v37, 31, v36
	v_lshl_add_u64 v[36:37], s[12:13], 0, v[36:37]
	v_pk_mul_f32 v[34:35], v[6:7], v[34:35]
	v_pk_add_f32 v[32:33], v[32:33], v[12:13]
	global_store_dword v[36:37], v38, off
	v_cvt_pk_bf16_f32 v38, v34, v35
	v_pk_add_f32 v[34:35], v[32:33], v[4:5] neg_lo:[0,1] neg_hi:[0,1]
	v_pk_add_f32 v[32:33], v[4:5], v[32:33] neg_lo:[0,1] neg_hi:[0,1]
	v_mul_f32_e32 v34, 0x3fb8aa3b, v34
	v_mul_f32_e32 v35, 0x3fb8aa3b, v35
	v_exp_f32_e32 v34, v34
	v_exp_f32_e32 v35, v35
	v_mul_f32_e32 v32, 0x3fb8aa3b, v32
	v_mul_f32_e32 v33, 0x3fb8aa3b, v33
	v_exp_f32_e32 v32, v32
	v_exp_f32_e32 v33, v33
	v_lshlrev_b32_e32 v36, 16, v116
	v_and_b32_e32 v37, 0xffff0000, v116
	v_pk_mul_f32 v[34:35], v[34:35], v[36:37]
	v_lshlrev_b32_e32 v36, 16, v115
	v_and_b32_e32 v37, 0xffff0000, v115
	v_pk_mul_f32 v[32:33], v[32:33], v[36:37]
	v_cvt_pk_bf16_f32 v36, v34, v35
	v_cvt_pk_bf16_f32 v37, v32, v33
	v_pk_mul_f32 v[34:35], v[8:9], v[34:35]
	ds_write_b32 v18, v37 offset:35904
	v_cvt_pk_bf16_f32 v37, v34, v35
	v_lshl_or_b32 v34, v114, 9, v45
	v_ashrrev_i32_e32 v35, 31, v34
	v_lshl_add_u64 v[34:35], s[12:13], 0, v[34:35]
	v_pk_mul_f32 v[32:33], v[6:7], v[32:33]
	v_pk_add_f32 v[30:31], v[30:31], v[12:13]
	global_store_dword v[34:35], v37, off
	v_cvt_pk_bf16_f32 v37, v32, v33
	v_pk_add_f32 v[32:33], v[30:31], v[4:5] neg_lo:[0,1] neg_hi:[0,1]
	v_pk_add_f32 v[30:31], v[4:5], v[30:31] neg_lo:[0,1] neg_hi:[0,1]
	v_mul_f32_e32 v32, 0x3fb8aa3b, v32
	v_mul_f32_e32 v33, 0x3fb8aa3b, v33
	v_exp_f32_e32 v32, v32
	v_exp_f32_e32 v33, v33
	v_mul_f32_e32 v30, 0x3fb8aa3b, v30
	v_mul_f32_e32 v31, 0x3fb8aa3b, v31
	v_exp_f32_e32 v30, v30
	v_exp_f32_e32 v31, v31
	v_lshlrev_b32_e32 v34, 16, v113
	v_and_b32_e32 v35, 0xffff0000, v113
	v_pk_mul_f32 v[32:33], v[32:33], v[34:35]
	v_lshlrev_b32_e32 v34, 16, v112
	v_and_b32_e32 v35, 0xffff0000, v112
	v_pk_mul_f32 v[30:31], v[30:31], v[34:35]
	v_cvt_pk_bf16_f32 v34, v32, v33
	v_add_u32_e32 v35, 0x800, v18
	ds_write2_b32 v35, v36, v34 offset0:16 offset1:148
	v_cvt_pk_bf16_f32 v34, v30, v31
	v_pk_mul_f32 v[30:31], v[6:7], v[30:31]
	v_pk_add_f32 v[28:29], v[28:29], v[12:13]
	v_cvt_pk_bf16_f32 v39, v30, v31
	v_pk_add_f32 v[30:31], v[28:29], v[4:5] neg_lo:[0,1] neg_hi:[0,1]
	v_pk_mul_f32 v[32:33], v[8:9], v[32:33]
	v_mul_f32_e32 v30, 0x3fb8aa3b, v30
	v_mul_f32_e32 v31, 0x3fb8aa3b, v31
	v_pk_add_f32 v[28:29], v[4:5], v[28:29] neg_lo:[0,1] neg_hi:[0,1]
	v_cvt_pk_bf16_f32 v35, v32, v33
	v_lshl_or_b32 v32, v111, 9, v45
	v_exp_f32_e32 v30, v30
	v_exp_f32_e32 v31, v31
	v_mul_f32_e32 v28, 0x3fb8aa3b, v28
	v_mul_f32_e32 v29, 0x3fb8aa3b, v29
	v_ashrrev_i32_e32 v33, 31, v32
	v_exp_f32_e32 v28, v28
	v_exp_f32_e32 v29, v29
	v_lshl_add_u64 v[32:33], s[12:13], 0, v[32:33]
	global_store_dword v[32:33], v35, off
	v_lshlrev_b32_e32 v32, 16, v110
	v_and_b32_e32 v33, 0xffff0000, v110
	v_pk_mul_f32 v[30:31], v[30:31], v[32:33]
	v_lshlrev_b32_e32 v32, 16, v109
	v_and_b32_e32 v33, 0xffff0000, v109
	v_pk_mul_f32 v[28:29], v[28:29], v[32:33]
	v_cvt_pk_bf16_f32 v40, v30, v31
	v_cvt_pk_bf16_f32 v32, v28, v29
	v_add_u32_e32 v33, 0x8e00, v18
	v_pk_mul_f32 v[30:31], v[8:9], v[30:31]
	ds_write2_b32 v33, v34, v32 offset0:20 offset1:152
	v_cvt_pk_bf16_f32 v32, v30, v31
	v_lshl_or_b32 v30, v108, 9, v45
	v_ashrrev_i32_e32 v31, 31, v30
	v_pk_mul_f32 v[28:29], v[6:7], v[28:29]
	v_lshl_add_u64 v[30:31], s[12:13], 0, v[30:31]
	v_cvt_pk_bf16_f32 v28, v28, v29
	v_lshlrev_b32_e32 v29, 16, v47
	global_store_dword v[30:31], v32, off
	v_and_or_b32 v30, v48, s35, v29
	v_lshlrev_b32_e32 v29, 16, v42
	v_and_or_b32 v31, v19, s35, v29
	v_lshlrev_b32_e32 v29, 16, v37
	v_lshrrev_b32_e32 v19, 16, v19
	v_and_or_b32 v32, v38, s35, v29
	v_lshlrev_b32_e32 v29, 16, v28
	v_and_or_b32 v35, v42, s88, v19
	v_lshrrev_b32_e32 v19, 16, v38
	v_add_lshl_u32 v38, v50, v104, 1
	v_and_or_b32 v33, v39, s35, v29
	v_lshrrev_b32_e32 v29, 16, v48
	v_and_or_b32 v36, v37, s88, v19
	v_lshrrev_b32_e32 v19, 16, v39
	v_ashrrev_i32_e32 v39, 31, v38
	v_and_or_b32 v34, v47, s88, v29
	v_and_or_b32 v37, v28, s88, v19
	v_lshl_add_u64 v[28:29], s[14:15], 0, v[38:39]
	v_pk_add_f32 v[26:27], v[26:27], v[12:13]
	global_store_dwordx4 v[28:29], v[30:33], off
	v_pk_add_f32 v[24:25], v[24:25], v[12:13]
	v_pk_add_f32 v[22:23], v[22:23], v[12:13]
	v_pk_add_f32 v[32:33], v[26:27], v[4:5] neg_lo:[0,1] neg_hi:[0,1]
	v_pk_add_f32 v[26:27], v[4:5], v[26:27] neg_lo:[0,1] neg_hi:[0,1]
	v_mul_f32_e32 v19, 0x3fb8aa3b, v32
	v_exp_f32_e32 v32, v19
	v_mul_f32_e32 v19, 0x3fb8aa3b, v33
	v_exp_f32_e32 v33, v19
	v_mul_f32_e32 v19, 0x3fb8aa3b, v26
	v_add_u32_e32 v30, 0x80, v38
	v_exp_f32_e32 v26, v19
	v_mul_f32_e32 v19, 0x3fb8aa3b, v27
	v_ashrrev_i32_e32 v31, 31, v30
	v_exp_f32_e32 v27, v19
	v_lshl_add_u64 v[30:31], s[14:15], 0, v[30:31]
	global_store_dwordx4 v[30:31], v[34:37], off
	v_pk_add_f32 v[20:21], v[20:21], v[12:13]
	v_pk_add_f32 v[16:17], v[16:17], v[12:13]
	v_lshlrev_b32_e32 v34, 16, v107
	v_and_b32_e32 v35, 0xffff0000, v107
	v_pk_mul_f32 v[32:33], v[32:33], v[34:35]
	v_lshlrev_b32_e32 v34, 16, v106
	v_and_b32_e32 v35, 0xffff0000, v106
	v_pk_mul_f32 v[26:27], v[26:27], v[34:35]
	v_cvt_pk_bf16_f32 v19, v32, v33
	v_add_u32_e32 v34, 0xc00, v18
	v_pk_mul_f32 v[32:33], v[8:9], v[32:33]
	ds_write2_b32 v34, v40, v19 offset0:24 offset1:156
	v_cvt_pk_bf16_f32 v34, v32, v33
	v_lshl_or_b32 v32, v105, 9, v45
	v_ashrrev_i32_e32 v33, 31, v32
	v_cvt_pk_bf16_f32 v19, v26, v27
	v_lshl_add_u64 v[32:33], s[12:13], 0, v[32:33]
	v_pk_mul_f32 v[26:27], v[6:7], v[26:27]
	global_store_dword v[32:33], v34, off
	v_cvt_pk_bf16_f32 v34, v26, v27
	v_pk_add_f32 v[26:27], v[24:25], v[4:5] neg_lo:[0,1] neg_hi:[0,1]
	v_pk_add_f32 v[24:25], v[4:5], v[24:25] neg_lo:[0,1] neg_hi:[0,1]
	v_mul_f32_e32 v26, 0x3fb8aa3b, v26
	v_mul_f32_e32 v27, 0x3fb8aa3b, v27
	v_exp_f32_e32 v26, v26
	v_exp_f32_e32 v27, v27
	v_mul_f32_e32 v24, 0x3fb8aa3b, v24
	v_mul_f32_e32 v25, 0x3fb8aa3b, v25
	v_exp_f32_e32 v24, v24
	v_exp_f32_e32 v25, v25
	v_lshlrev_b32_e32 v32, 16, v103
	v_and_b32_e32 v33, 0xffff0000, v103
	v_pk_mul_f32 v[26:27], v[26:27], v[32:33]
	v_lshlrev_b32_e32 v32, 16, v102
	v_and_b32_e32 v33, 0xffff0000, v102
	v_pk_mul_f32 v[24:25], v[24:25], v[32:33]
	v_cvt_pk_bf16_f32 v32, v26, v27
	v_cvt_pk_bf16_f32 v33, v24, v25
	v_add_u32_e32 v35, 0x9200, v18
	v_pk_mul_f32 v[26:27], v[8:9], v[26:27]
	ds_write2_b32 v35, v19, v33 offset0:28 offset1:160
	v_cvt_pk_bf16_f32 v19, v26, v27
	v_lshl_or_b32 v26, v101, 9, v45
	v_ashrrev_i32_e32 v27, 31, v26
	v_lshl_add_u64 v[26:27], s[12:13], 0, v[26:27]
	v_pk_mul_f32 v[24:25], v[6:7], v[24:25]
	global_store_dword v[26:27], v19, off
	v_cvt_pk_bf16_f32 v19, v24, v25
	v_pk_add_f32 v[24:25], v[22:23], v[4:5] neg_lo:[0,1] neg_hi:[0,1]
	v_pk_add_f32 v[22:23], v[4:5], v[22:23] neg_lo:[0,1] neg_hi:[0,1]
	v_mul_f32_e32 v24, 0x3fb8aa3b, v24
	v_mul_f32_e32 v25, 0x3fb8aa3b, v25
	v_exp_f32_e32 v24, v24
	v_exp_f32_e32 v25, v25
	v_mul_f32_e32 v22, 0x3fb8aa3b, v22
	v_mul_f32_e32 v23, 0x3fb8aa3b, v23
	v_exp_f32_e32 v22, v22
	v_exp_f32_e32 v23, v23
	v_lshlrev_b32_e32 v26, 16, v100
	v_and_b32_e32 v27, 0xffff0000, v100
	v_pk_mul_f32 v[24:25], v[24:25], v[26:27]
	v_lshlrev_b32_e32 v26, 16, v99
	v_and_b32_e32 v27, 0xffff0000, v99
	v_pk_mul_f32 v[22:23], v[22:23], v[26:27]
	v_cvt_pk_bf16_f32 v26, v24, v25
	v_add_u32_e32 v27, 0x1000, v18
	v_pk_mul_f32 v[24:25], v[8:9], v[24:25]
	ds_write2_b32 v27, v32, v26 offset0:32 offset1:164
	v_cvt_pk_bf16_f32 v27, v24, v25
	v_lshl_or_b32 v24, v98, 9, v45
	v_ashrrev_i32_e32 v25, 31, v24
	v_cvt_pk_bf16_f32 v26, v22, v23
	v_lshl_add_u64 v[24:25], s[12:13], 0, v[24:25]
	v_pk_mul_f32 v[22:23], v[6:7], v[22:23]
	global_store_dword v[24:25], v27, off
	v_cvt_pk_bf16_f32 v27, v22, v23
	v_pk_add_f32 v[22:23], v[20:21], v[4:5] neg_lo:[0,1] neg_hi:[0,1]
	v_pk_add_f32 v[20:21], v[4:5], v[20:21] neg_lo:[0,1] neg_hi:[0,1]
	v_mul_f32_e32 v22, 0x3fb8aa3b, v22
	v_mul_f32_e32 v23, 0x3fb8aa3b, v23
	v_exp_f32_e32 v22, v22
	v_exp_f32_e32 v23, v23
	v_mul_f32_e32 v20, 0x3fb8aa3b, v20
	v_mul_f32_e32 v21, 0x3fb8aa3b, v21
	v_exp_f32_e32 v20, v20
	v_exp_f32_e32 v21, v21
	v_lshlrev_b32_e32 v24, 16, v97
	v_and_b32_e32 v25, 0xffff0000, v97
	v_pk_mul_f32 v[22:23], v[22:23], v[24:25]
	v_lshlrev_b32_e32 v24, 16, v96
	v_and_b32_e32 v25, 0xffff0000, v96
	v_pk_mul_f32 v[20:21], v[20:21], v[24:25]
	v_cvt_pk_bf16_f32 v24, v22, v23
	v_cvt_pk_bf16_f32 v25, v20, v21
	v_add_u32_e32 v32, 0x9600, v18
	v_pk_mul_f32 v[22:23], v[8:9], v[22:23]
	ds_write2_b32 v32, v26, v25 offset0:36 offset1:168
	v_cvt_pk_bf16_f32 v25, v22, v23
	v_lshl_or_b32 v22, v95, 9, v45
	v_ashrrev_i32_e32 v23, 31, v22
	v_lshl_add_u64 v[22:23], s[12:13], 0, v[22:23]
	v_pk_mul_f32 v[20:21], v[6:7], v[20:21]
	global_store_dword v[22:23], v25, off
	v_cvt_pk_bf16_f32 v25, v20, v21
	v_pk_add_f32 v[20:21], v[16:17], v[4:5] neg_lo:[0,1] neg_hi:[0,1]
	v_pk_add_f32 v[16:17], v[4:5], v[16:17] neg_lo:[0,1] neg_hi:[0,1]
	v_mul_f32_e32 v20, 0x3fb8aa3b, v20
	v_mul_f32_e32 v21, 0x3fb8aa3b, v21
	v_exp_f32_e32 v20, v20
	v_exp_f32_e32 v21, v21
	v_mul_f32_e32 v16, 0x3fb8aa3b, v16
	v_mul_f32_e32 v17, 0x3fb8aa3b, v17
	v_exp_f32_e32 v16, v16
	v_exp_f32_e32 v17, v17
	v_lshlrev_b32_e32 v22, 16, v94
	v_and_b32_e32 v23, 0xffff0000, v94
	v_pk_mul_f32 v[20:21], v[20:21], v[22:23]
	v_lshlrev_b32_e32 v22, 16, v93
	v_and_b32_e32 v23, 0xffff0000, v93
	v_pk_mul_f32 v[16:17], v[16:17], v[22:23]
	v_cvt_pk_bf16_f32 v22, v20, v21
	v_add_u32_e32 v23, 0x1400, v18
	v_pk_mul_f32 v[20:21], v[8:9], v[20:21]
	ds_write2_b32 v23, v24, v22 offset0:40 offset1:172
	v_cvt_pk_bf16_f32 v23, v20, v21
	v_lshl_or_b32 v20, v92, 9, v45
	v_ashrrev_i32_e32 v21, 31, v20
	v_cvt_pk_bf16_f32 v22, v16, v17
	v_lshl_add_u64 v[20:21], s[12:13], 0, v[20:21]
	v_pk_mul_f32 v[16:17], v[6:7], v[16:17]
	v_pk_add_f32 v[14:15], v[12:13], v[14:15]
	global_store_dword v[20:21], v23, off
	v_cvt_pk_bf16_f32 v23, v16, v17
	v_pk_add_f32 v[16:17], v[14:15], v[4:5] neg_lo:[0,1] neg_hi:[0,1]
	v_pk_add_f32 v[14:15], v[4:5], v[14:15] neg_lo:[0,1] neg_hi:[0,1]
	v_mul_f32_e32 v16, 0x3fb8aa3b, v16
	v_mul_f32_e32 v17, 0x3fb8aa3b, v17
	v_exp_f32_e32 v16, v16
	v_exp_f32_e32 v17, v17
	v_mul_f32_e32 v14, 0x3fb8aa3b, v14
	v_mul_f32_e32 v15, 0x3fb8aa3b, v15
	v_exp_f32_e32 v14, v14
	v_exp_f32_e32 v15, v15
	v_lshlrev_b32_e32 v20, 16, v91
	v_and_b32_e32 v21, 0xffff0000, v91
	v_pk_mul_f32 v[16:17], v[16:17], v[20:21]
	v_lshlrev_b32_e32 v20, 16, v90
	v_and_b32_e32 v21, 0xffff0000, v90
	v_pk_mul_f32 v[14:15], v[14:15], v[20:21]
	v_cvt_pk_bf16_f32 v20, v16, v17
	v_cvt_pk_bf16_f32 v21, v14, v15
	v_add_u32_e32 v24, 0x9a00, v18
	v_pk_mul_f32 v[16:17], v[8:9], v[16:17]
	ds_write2_b32 v24, v22, v21 offset0:44 offset1:176
	v_cvt_pk_bf16_f32 v21, v16, v17
	v_lshl_or_b32 v16, v89, 9, v45
	v_ashrrev_i32_e32 v17, 31, v16
	v_lshl_add_u64 v[16:17], s[12:13], 0, v[16:17]
	v_pk_mul_f32 v[14:15], v[6:7], v[14:15]
	v_pk_add_f32 v[10:11], v[12:13], v[10:11]
	global_store_dword v[16:17], v21, off
	v_cvt_pk_bf16_f32 v21, v14, v15
	v_pk_add_f32 v[14:15], v[10:11], v[4:5] neg_lo:[0,1] neg_hi:[0,1]
	v_pk_add_f32 v[10:11], v[4:5], v[10:11] neg_lo:[0,1] neg_hi:[0,1]
	v_mul_f32_e32 v14, 0x3fb8aa3b, v14
	v_mul_f32_e32 v15, 0x3fb8aa3b, v15
	v_exp_f32_e32 v14, v14
	v_exp_f32_e32 v15, v15
	v_mul_f32_e32 v10, 0x3fb8aa3b, v10
	v_mul_f32_e32 v11, 0x3fb8aa3b, v11
	v_exp_f32_e32 v10, v10
	v_exp_f32_e32 v11, v11
	v_lshlrev_b32_e32 v16, 16, v88
	v_and_b32_e32 v17, 0xffff0000, v88
	v_pk_mul_f32 v[14:15], v[14:15], v[16:17]
	v_lshlrev_b32_e32 v16, 16, v87
	v_and_b32_e32 v17, 0xffff0000, v87
	v_pk_mul_f32 v[10:11], v[10:11], v[16:17]
	v_cvt_pk_bf16_f32 v16, v14, v15
	v_add_u32_e32 v17, 0x1800, v18
	v_pk_mul_f32 v[14:15], v[8:9], v[14:15]
	ds_write2_b32 v17, v20, v16 offset0:48 offset1:180
	v_cvt_pk_bf16_f32 v17, v14, v15
	v_lshl_or_b32 v14, v86, 9, v45
	v_ashrrev_i32_e32 v15, 31, v14
	v_cvt_pk_bf16_f32 v16, v10, v11
	v_lshl_add_u64 v[14:15], s[12:13], 0, v[14:15]
	v_pk_mul_f32 v[10:11], v[6:7], v[10:11]
	v_pk_add_f32 v[2:3], v[12:13], v[2:3]
	global_store_dword v[14:15], v17, off
	v_cvt_pk_bf16_f32 v14, v10, v11
	v_pk_add_f32 v[10:11], v[2:3], v[4:5] neg_lo:[0,1] neg_hi:[0,1]
	v_pk_add_f32 v[2:3], v[4:5], v[2:3] neg_lo:[0,1] neg_hi:[0,1]
	v_mul_f32_e32 v10, 0x3fb8aa3b, v10
	v_mul_f32_e32 v11, 0x3fb8aa3b, v11
	v_exp_f32_e32 v10, v10
	v_exp_f32_e32 v11, v11
	v_mul_f32_e32 v2, 0x3fb8aa3b, v2
	v_mul_f32_e32 v3, 0x3fb8aa3b, v3
	v_exp_f32_e32 v2, v2
	v_exp_f32_e32 v3, v3
	v_lshlrev_b32_e32 v4, 16, v85
	v_and_b32_e32 v5, 0xffff0000, v85
	v_pk_mul_f32 v[4:5], v[10:11], v[4:5]
	v_lshlrev_b32_e32 v10, 16, v84
	v_and_b32_e32 v11, 0xffff0000, v84
	v_pk_mul_f32 v[2:3], v[2:3], v[10:11]
	v_cvt_pk_bf16_f32 v10, v4, v5
	v_pk_mul_f32 v[4:5], v[8:9], v[4:5]
	ds_write_b32 v18, v10 offset:7392
	v_cvt_pk_bf16_f32 v8, v4, v5
	v_lshl_or_b32 v4, v83, 9, v45
	v_ashrrev_i32_e32 v5, 31, v4
	v_cvt_pk_bf16_f32 v10, v2, v3
	v_lshl_add_u64 v[4:5], s[12:13], 0, v[4:5]
	v_pk_mul_f32 v[2:3], v[6:7], v[2:3]
	v_add_u32_e32 v11, 0x9e00, v18
	global_store_dword v[4:5], v8, off
	v_cvt_pk_bf16_f32 v9, v2, v3
	v_lshlrev_b32_e32 v2, 16, v19
	v_lshlrev_b32_e32 v3, 16, v25
	v_and_b32_e32 v4, 0xffff, v23
	v_and_b32_e32 v5, 0xffff, v14
	s_movk_i32 s0, 0x80
	ds_write2_b32 v11, v16, v10 offset0:52 offset1:184
	v_and_or_b32 v2, v34, s35, v2
	v_and_or_b32 v3, v27, s35, v3
	v_lshl_or_b32 v4, v21, 16, v4
	v_lshl_or_b32 v5, v9, 16, v5
	v_lshrrev_b32_e32 v6, 16, v34
	v_lshrrev_b32_e32 v7, 16, v27
	v_lshrrev_b32_e32 v8, 16, v23
	v_lshrrev_b32_e32 v10, 16, v14
	v_cmp_gt_u32_e32 vcc, s0, v82
	v_and_or_b32 v6, v19, s88, v6
	v_and_or_b32 v7, v25, s88, v7
	v_and_or_b32 v8, v21, s88, v8
	v_and_or_b32 v9, v9, s88, v10
	global_store_dwordx4 v[28:29], v[2:5], off offset:16
	global_store_dwordx4 v[30:31], v[6:9], off offset:16
	s_and_saveexec_b64 s[12:13], vcc
	s_cbranch_execz .LBB0_288
	v_mul_f32_e32 v0, 0x3fb8aa3b, v0
	v_mul_f32_e32 v1, 0x3fb8aa3b, v1
	v_exp_f32_e32 v0, v0
	v_exp_f32_e32 v1, v1
	v_add_u32_e32 v2, 0x22400, v44
	ds_write_b64 v2, v[0:1]

.LBB0_304:
	v_add_u32_e32 v33, v0, v190
	v_cvt_f32_ubyte0_e32 v0, s0
	v_rcp_iflag_f32_e32 v0, v0
	s_sub_i32 s13, 0, s0
	s_abs_i32 s12, s2
	s_ashr_i32 s3, s2, 31
	v_mul_f32_e32 v0, 0x4f7ffffe, v0
	v_cvt_u32_f32_e32 v0, v0
	v_ashrrev_i32_e32 v34, 6, v33
	v_add_u32_e32 v4, 0x200, v33
	v_ashrrev_i32_e32 v36, 6, v4
	v_readfirstlane_b32 s14, v0
	s_mul_i32 s13, s13, s14
	s_mul_hi_u32 s13, s14, s13
	s_add_i32 s14, s14, s13
	s_mul_hi_u32 s13, s12, s14
	s_mul_i32 s14, s13, s0
	s_sub_i32 s12, s12, s14
	s_add_i32 s14, s13, 1
	s_sub_i32 s15, s12, s0
	s_cmp_ge_u32 s12, s0
	s_cselect_b32 s13, s14, s13
	s_cselect_b32 s12, s15, s12
	s_add_i32 s14, s13, 1
	s_cmp_ge_u32 s12, s0
	s_cselect_b32 s12, s14, s13
	s_xor_b32 s12, s12, s3
	s_sub_i32 s3, s12, s3
	s_mul_i32 s0, s3, s0
	s_sub_i32 s0, s2, s0
	s_lshl_b32 s14, s0, 8
	s_ashr_i32 s15, s14, 31
	s_lshl_b32 s12, s3, 6
	s_lshl_b64 s[2:3], s[14:15], 2
	s_add_u32 s2, s18, s2
	v_lshlrev_b32_e32 v0, 4, v33
	s_addc_u32 s3, s19, s3
	v_and_b32_e32 v64, 0x3f0, v0
	v_add_u32_e32 v0, s12, v34
	v_add_u32_e32 v8, 0x400, v33
	v_lshl_add_u64 v[28:29], s[2:3], 0, v[64:65]
	v_mad_i64_i32 v[0:1], s[2:3], s16, v0, 0
	v_add_u32_e32 v4, s12, v36
	v_ashrrev_i32_e32 v37, 6, v8
	v_add_u32_e32 v12, 0x600, v33
	v_lshl_add_u64 v[0:1], v[0:1], 2, v[28:29]
	v_mad_i64_i32 v[4:5], s[2:3], s16, v4, 0
	v_add_u32_e32 v8, s12, v37
	v_ashrrev_i32_e32 v38, 6, v12
	v_add_u32_e32 v16, 0x800, v33
	v_lshl_add_u64 v[4:5], v[4:5], 2, v[28:29]
	v_mad_i64_i32 v[8:9], s[2:3], s16, v8, 0
	v_add_u32_e32 v12, s12, v38
	v_ashrrev_i32_e32 v39, 6, v16
	v_add_u32_e32 v20, 0xa00, v33
	v_lshl_add_u64 v[8:9], v[8:9], 2, v[28:29]
	v_mad_i64_i32 v[12:13], s[2:3], s16, v12, 0
	v_add_u32_e32 v16, s12, v39
	v_ashrrev_i32_e32 v40, 6, v20
	v_add_u32_e32 v24, 0xc00, v33
	v_lshl_add_u64 v[12:13], v[12:13], 2, v[28:29]
	v_mad_i64_i32 v[16:17], s[2:3], s16, v16, 0
	v_add_u32_e32 v20, s12, v40
	v_ashrrev_i32_e32 v41, 6, v24
	v_add_u32_e32 v30, 0xe00, v33
	v_lshl_add_u64 v[16:17], v[16:17], 2, v[28:29]
	v_mad_i64_i32 v[20:21], s[2:3], s16, v20, 0
	v_add_u32_e32 v24, s12, v41
	v_ashrrev_i32_e32 v42, 6, v30
	v_lshl_add_u64 v[20:21], v[20:21], 2, v[28:29]
	v_mad_i64_i32 v[24:25], s[2:3], s16, v24, 0
	v_add_u32_e32 v30, s12, v42
	v_lshl_add_u64 v[24:25], v[24:25], 2, v[28:29]
	v_mad_i64_i32 v[30:31], s[2:3], s16, v30, 0
	v_lshl_add_u64 v[28:29], v[30:31], 2, v[28:29]
	v_add_u32_e32 v32, 0, v64
	s_movk_i32 s0, 0x410
	v_mad_u64_u32 v[34:35], s[2:3], v34, s0, v[32:33]
	s_ashr_i32 s13, s12, 31
	s_waitcnt vmcnt(2)
	ds_write_b128 v34, v[192:195]
	v_mad_u64_u32 v[0:1], s[2:3], v36, s0, v[32:33]
	v_ashrrev_i32_e32 v2, 1, v33
	v_lshlrev_b32_e32 v3, 5, v33
	v_and_b32_e32 v3, 32, v3
	v_lshlrev_b32_e32 v64, 1, v3
	ds_write_b128 v0, v[196:199]
	v_mad_u64_u32 v[0:1], s[2:3], v37, s0, v[32:33]
	ds_write_b128 v0, v[200:203]
	v_mad_u64_u32 v[0:1], s[2:3], v38, s0, v[32:33]
	ds_write_b128 v0, v[204:207]
	v_mad_u64_u32 v[0:1], s[2:3], v39, s0, v[32:33]
	ds_write_b128 v0, v[208:211]
	v_mad_u64_u32 v[0:1], s[2:3], v40, s0, v[32:33]
	ds_write_b128 v0, v[212:215]
	v_mad_u64_u32 v[0:1], s[2:3], v41, s0, v[32:33]
	ds_write_b128 v0, v[216:219]
	v_mad_u64_u32 v[0:1], s[2:3], v42, s0, v[32:33]
	ds_write_b128 v0, v[220:223]
	v_add_u32_e32 v0, s14, v2
	v_ashrrev_i32_e32 v1, 31, v0
	v_lshlrev_b64 v[0:1], 12, v[0:1]
	v_lshl_add_u64 v[0:1], s[10:11], 0, v[0:1]
	v_lshl_add_u64 v[0:1], s[12:13], 1, v[0:1]
	s_movk_i32 s0, 0x104
	v_lshl_add_u64 v[4:5], v[0:1], 0, v[64:65]
	v_mad_u32_u24 v0, v3, s0, v2
	v_lshl_add_u32 v6, v0, 2, 0
	s_waitcnt lgkmcnt(0)
	s_barrier
	ds_read_b32 v0, v6
	ds_read_b32 v1, v6 offset:1040
	ds_read_b32 v2, v6 offset:2080
	ds_read_b32 v3, v6 offset:3120
	ds_read_b32 v7, v6 offset:4160
	ds_read_b32 v8, v6 offset:5200
	ds_read_b32 v9, v6 offset:6240
	ds_read_b32 v10, v6 offset:7280
	s_waitcnt lgkmcnt(6)
	v_cvt_pk_bf16_f32 v0, v0, v1
	s_waitcnt lgkmcnt(4)
	v_cvt_pk_bf16_f32 v1, v2, v3
	s_waitcnt lgkmcnt(2)
	v_cvt_pk_bf16_f32 v2, v7, v8
	s_waitcnt lgkmcnt(0)
	v_cvt_pk_bf16_f32 v3, v9, v10
	global_store_dwordx4 v[4:5], v[0:3], off
	ds_read_b32 v0, v6 offset:8320
	ds_read_b32 v1, v6 offset:9360
	ds_read_b32 v2, v6 offset:10400
	ds_read_b32 v3, v6 offset:11440
	ds_read_b32 v7, v6 offset:12480
	ds_read_b32 v8, v6 offset:13520
	ds_read_b32 v9, v6 offset:14560
	ds_read_b32 v10, v6 offset:15600
	s_waitcnt lgkmcnt(6)
	v_cvt_pk_bf16_f32 v0, v0, v1
	s_waitcnt lgkmcnt(4)
	v_cvt_pk_bf16_f32 v1, v2, v3
	s_waitcnt lgkmcnt(2)
	v_cvt_pk_bf16_f32 v2, v7, v8
	s_waitcnt lgkmcnt(0)
	v_cvt_pk_bf16_f32 v3, v9, v10
	global_store_dwordx4 v[4:5], v[0:3], off offset:16
	ds_read_b32 v0, v6 offset:16640
	ds_read_b32 v1, v6 offset:17680
	ds_read_b32 v2, v6 offset:18720
	ds_read_b32 v3, v6 offset:19760
	ds_read_b32 v7, v6 offset:20800
	ds_read_b32 v8, v6 offset:21840
	ds_read_b32 v9, v6 offset:22880
	ds_read_b32 v10, v6 offset:23920
	s_waitcnt lgkmcnt(6)
	v_cvt_pk_bf16_f32 v0, v0, v1
	s_waitcnt lgkmcnt(4)
	v_cvt_pk_bf16_f32 v1, v2, v3
	s_waitcnt lgkmcnt(2)
	v_cvt_pk_bf16_f32 v2, v7, v8
	s_waitcnt lgkmcnt(0)
	v_cvt_pk_bf16_f32 v3, v9, v10
	global_store_dwordx4 v[4:5], v[0:3], off offset:32
	ds_read_b32 v0, v6 offset:24960
	ds_read_b32 v1, v6 offset:26000
	ds_read_b32 v2, v6 offset:27040
	ds_read_b32 v3, v6 offset:28080
	ds_read_b32 v7, v6 offset:29120
	ds_read_b32 v8, v6 offset:30160
	ds_read_b32 v9, v6 offset:31200
	ds_read_b32 v6, v6 offset:32240
	s_waitcnt lgkmcnt(6)
	v_cvt_pk_bf16_f32 v0, v0, v1
	s_waitcnt lgkmcnt(4)
	v_cvt_pk_bf16_f32 v1, v2, v3
	s_waitcnt lgkmcnt(2)
	v_cvt_pk_bf16_f32 v2, v7, v8
	s_waitcnt lgkmcnt(0)
	v_cvt_pk_bf16_f32 v3, v9, v6
	global_store_dwordx4 v[4:5], v[0:3], off offset:48
	s_barrier

	.amdhsa_kernel _Z6mk_fwd4Args
		.amdhsa_group_segment_fixed_size 0
		.amdhsa_private_segment_fixed_size 0
		.amdhsa_kernarg_size 424
		.amdhsa_user_sgpr_count 2
		.amdhsa_user_sgpr_dispatch_ptr 0
		.amdhsa_user_sgpr_queue_ptr 0
		.amdhsa_user_sgpr_kernarg_segment_ptr 1
		.amdhsa_user_sgpr_dispatch_id 0
		.amdhsa_user_sgpr_kernarg_preload_length 0
		.amdhsa_user_sgpr_kernarg_preload_offset 0
		.amdhsa_user_sgpr_private_segment_size 0
		.amdhsa_uses_dynamic_stack 0
		.amdhsa_enable_private_segment 0
		.amdhsa_system_sgpr_workgroup_id_x 1
		.amdhsa_system_sgpr_workgroup_id_y 0
		.amdhsa_system_sgpr_workgroup_id_z 0
		.amdhsa_system_sgpr_workgroup_info 0
		.amdhsa_system_vgpr_workitem_id 2
		.amdhsa_next_free_vgpr 256
		.amdhsa_next_free_sgpr 102
		.amdhsa_accum_offset 256
		.amdhsa_reserve_vcc 1
		.amdhsa_float_round_mode_32 0
		.amdhsa_float_round_mode_16_64 0
		.amdhsa_float_denorm_mode_32 3
		.amdhsa_float_denorm_mode_16_64 3
		.amdhsa_dx10_clamp 1
		.amdhsa_ieee_mode 1
		.amdhsa_fp16_overflow 0
		.amdhsa_tg_split 0
		.amdhsa_exception_fp_ieee_invalid_op 0
		.amdhsa_exception_fp_denorm_src 0
		.amdhsa_exception_fp_ieee_div_zero 0
		.amdhsa_exception_fp_ieee_overflow 0
		.amdhsa_exception_fp_ieee_underflow 0
		.amdhsa_exception_fp_ieee_inexact 0
		.amdhsa_exception_int_div_zero 0
	.end_amdhsa_kernel

amdhsa.kernels:
  - .agpr_count:     0
    .args:
      - .offset:         0
        .size:           168
        .value_kind:     by_value
      - .offset:         168
        .size:           4
        .value_kind:     hidden_block_count_x
      - .offset:         172
        .size:           4
        .value_kind:     hidden_block_count_y
      - .offset:         176
        .size:           4
        .value_kind:     hidden_block_count_z
      - .offset:         180
        .size:           2
        .value_kind:     hidden_group_size_x
      - .offset:         182
        .size:           2
        .value_kind:     hidden_group_size_y
      - .offset:         184
        .size:           2
        .value_kind:     hidden_group_size_z
      - .offset:         186
        .size:           2
        .value_kind:     hidden_remainder_x
      - .offset:         188
        .size:           2
        .value_kind:     hidden_remainder_y
      - .offset:         190
        .size:           2
        .value_kind:     hidden_remainder_z
      - .offset:         208
        .size:           8
        .value_kind:     hidden_global_offset_x
      - .offset:         216
        .size:           8
        .value_kind:     hidden_global_offset_y
      - .offset:         224
        .size:           8
        .value_kind:     hidden_global_offset_z
      - .offset:         232
        .size:           2
        .value_kind:     hidden_grid_dims
      - .offset:         256
        .size:           8
        .value_kind:     hidden_multigrid_sync_arg
      - .offset:         288
        .size:           4
        .value_kind:     hidden_dynamic_lds_size
    .group_segment_fixed_size: 0
    .kernarg_segment_align: 8
    .kernarg_segment_size: 424
    .language:       OpenCL C
    .language_version:
      - 2
      - 0
    .max_flat_workgroup_size: 512
    .name:           _Z6mk_fwd4Args
    .private_segment_fixed_size: 0
    .sgpr_count:     108
    .sgpr_spill_count: 240
    .symbol:         _Z6mk_fwd4Args.kd
    .uniform_work_group_size: 1
    .uses_dynamic_stack: false
    .vgpr_count:     256
    .vgpr_spill_count: 0
    .wavefront_size: 64
